# GLA pass A gate section rewritten by hand: 8-channel interleaved DPP scans, pipelined GU LDS reads
# baseline (speedup 1.0000x reference)
.LBB0_334:
	s_and_b32 s5, s5, 3
	v_lshlrev_b32_sdwa v16, v81, v82 dst_sel:DWORD dst_unused:UNUSED_PAD src0_sel:DWORD src1_sel:BYTE_0
	v_and_b32_e32 v83, 63, v82
	s_lshl_b32 s2, s5, 6
	v_and_b32_e32 v0, 0x300, v16
	v_or3_b32 v1, s2, v83, v0
	v_or_b32_sdwa v3, v82, s23 dst_sel:DWORD dst_unused:UNUSED_PAD src0_sel:BYTE_0 src1_sel:DWORD
	v_lshlrev_b32_e32 v2, 2, v1
	v_lshlrev_b32_e32 v1, 2, v3
	v_and_b32_e32 v1, 0x700, v1
	v_or3_b32 v1, v83, v1, s2
	v_or_b32_sdwa v8, v82, s25 dst_sel:DWORD dst_unused:UNUSED_PAD src0_sel:BYTE_0 src1_sel:DWORD
	v_lshlrev_b32_e32 v4, 2, v1
	v_lshlrev_b32_e32 v1, 2, v8
	v_and_b32_e32 v1, 0xb00, v1
	v_or3_b32 v1, v83, v1, s2
	v_or_b32_sdwa v12, v82, s24 dst_sel:DWORD dst_unused:UNUSED_PAD src0_sel:BYTE_0 src1_sel:DWORD
	v_lshlrev_b32_e32 v5, 2, v1
	v_lshlrev_b32_e32 v1, 2, v12
	v_and_b32_e32 v1, 0xf00, v1
	v_or3_b32 v0, v83, v0, s2
	v_or3_b32 v1, v83, v1, s2
	v_lshlrev_b32_e32 v64, 2, v0
	v_lshlrev_b32_e32 v6, 2, v1
	v_lshl_add_u64 v[0:1], s[56:57], 0, v[64:65]
	v_bitop3_b32 v7, v16, s27, v78 bitop3:0xc8
	v_bitop3_b32 v9, v16, s28, v79 bitop3:0xc8
	v_bitop3_b32 v10, v16, s29, v80 bitop3:0xc8
	v_add_co_u32_e32 v0, vcc, s26, v0
	v_or3_b32 v7, v83, v7, s2
	v_or3_b32 v9, v83, v9, s2
	v_or3_b32 v10, v83, v10, s2
	v_addc_co_u32_e32 v1, vcc, 0, v1, vcc
	v_lshlrev_b32_e32 v7, 2, v7
	v_lshlrev_b32_e32 v9, 2, v9
	v_lshlrev_b32_e32 v10, 2, v10
	global_load_dword v17, v2, s[56:57]
	global_load_dword v18, v4, s[56:57]
	global_load_dword v19, v5, s[56:57]
	global_load_dword v20, v6, s[56:57]
	global_load_dword v21, v[0:1], off
	global_load_dword v22, v7, s[56:57]
	global_load_dword v23, v9, s[56:57]
	global_load_dword v24, v10, s[56:57]
	v_lshlrev_b32_e32 v0, 4, v82
	v_bfe_u32 v25, v82, 4, 4
	v_and_b32_e32 v64, 0xf0, v0
	v_add_u32_e32 v0, s0, v25
	v_lshrrev_b32_e32 v26, 4, v3
	v_mad_i64_i32 v[0:1], s[2:3], v0, s30, v[66:67]
	v_add_u32_e32 v2, s0, v26
	v_lshrrev_b32_e32 v27, 4, v8
	s_lshl_b32 s2, s5, 8
	s_mov_b32 s3, s11
	v_mad_i64_i32 v[2:3], s[14:15], v2, s30, v[66:67]
	v_add_u32_e32 v8, s0, v27
	v_lshl_add_u64 v[0:1], v[0:1], 0, s[2:3]
	v_lshl_add_u64 v[2:3], v[2:3], 0, s[2:3]
	v_mad_i64_i32 v[8:9], s[14:15], v8, s30, v[66:67]
	v_lshl_add_u64 v[0:1], v[0:1], 0, v[64:65]
	v_lshl_add_u64 v[4:5], v[2:3], 0, v[64:65]
	v_lshl_add_u64 v[8:9], v[8:9], 0, s[2:3]
	v_lshrrev_b32_e32 v28, 4, v12
	global_load_dwordx4 v[0:3], v[0:1], off offset:1024
	s_nop 0
	global_load_dwordx4 v[4:7], v[4:5], off offset:1024
	v_lshl_add_u64 v[8:9], v[8:9], 0, v[64:65]
	v_add_u32_e32 v12, s0, v28
	global_load_dwordx4 v[8:11], v[8:9], off offset:1024
	v_mad_i64_i32 v[12:13], s[14:15], v12, s30, v[66:67]
	v_lshl_add_u64 v[12:13], v[12:13], 0, s[2:3]
	v_lshl_add_u64 v[12:13], v[12:13], 0, v[64:65]
	global_load_dwordx4 v[12:15], v[12:13], off offset:1024
	s_lshr_b32 s3, s37, 8
	s_mul_i32 s3, s3, 0xd000
	s_add_i32 s43, s3, 0
	v_add_u32_e32 v16, s43, v16
	s_lshl_b32 s14, s5, 7
	s_mov_b32 s15, s11
	s_waitcnt vmcnt(0)
	v_mul_f32_e32 v17, 0x3fb8aa3b, v17
	v_mul_f32_e32 v18, 0x3fb8aa3b, v18
	v_mul_f32_e32 v19, 0x3fb8aa3b, v19
	v_mul_f32_e32 v20, 0x3fb8aa3b, v20
	ds_write2st64_b32 v16, v17, v18 offset1:4
	ds_write2st64_b32 v16, v19, v20 offset0:8 offset1:12
	v_mul_f32_e32 v17, 0x3fb8aa3b, v21
	v_mul_f32_e32 v18, 0x3fb8aa3b, v22
	ds_write2st64_b32 v16, v17, v18 offset0:16 offset1:20
	v_mul_f32_e32 v17, 0x3fb8aa3b, v23
	v_mul_f32_e32 v18, 0x3fb8aa3b, v24
	ds_write2st64_b32 v16, v17, v18 offset0:24 offset1:28
	v_add_u32_e32 v16, s43, v64
	v_mad_u32_u24 v17, v25, s31, v16
	ds_write_b128 v17, v[0:3] offset:32768
	v_mad_u32_u24 v0, v26, s31, v16
	ds_write_b128 v0, v[4:7] offset:32768
	v_mad_u32_u24 v0, v27, s31, v16
	ds_write_b128 v0, v[8:11] offset:32768
	v_mad_u32_u24 v0, v28, s31, v16
	v_add_u32_e32 v16, s0, v83
	s_lshr_b32 s0, s37, 2
	s_and_b32 s0, s0, 48
	v_ashrrev_i32_e32 v17, 31, v16
	s_lshl_b32 s10, s0, 1
	ds_write_b128 v0, v[12:15] offset:32768
	v_lshlrev_b64 v[0:1], 7, v[16:17]
	v_mad_i64_i32 v[16:17], s[16:17], v16, s30, v[66:67]
	s_cmp_gt_i32 s36, 3
	s_cselect_b64 s[16:17], -1, 0
	s_and_b64 s[38:39], s[16:17], exec
	s_cselect_b32 s38, 0, 0x200
	s_mov_b32 s39, s11
	v_lshl_add_u64 v[18:19], v[16:17], 0, s[14:15]
	v_lshl_add_u64 v[16:17], v[16:17], 0, s[38:39]
	s_lshl_b32 s3, s4, 2
	v_lshl_add_u64 v[16:17], v[16:17], 0, s[14:15]
	s_or_b32 s47, s3, s5
	s_lshl_b32 s14, s0, 2
	s_lshl_b32 s42, s47, 1
	s_add_i32 s46, s43, s14
	s_add_u32 s38, s13, s14
	s_addc_u32 s39, s18, 0
	s_add_u32 s4, s58, s2
	v_lshl_add_u64 v[12:13], s[8:9], 0, v[0:1]
	v_lshl_add_u64 v[18:19], v[18:19], 0, s[10:11]
	v_lshl_add_u64 v[40:41], v[16:17], 0, s[10:11]
	s_addc_u32 s5, s59, 0
	v_mov_b32_e32 v52, s14
	global_load_dwordx4 v[24:27], v[12:13], off offset:48
	global_load_dwordx4 v[28:31], v[12:13], off offset:32
	global_load_dwordx4 v[32:35], v[12:13], off offset:16
	global_load_dwordx4 v[36:39], v[12:13], off
	global_load_dwordx4 v[0:3], v[12:13], off offset:112
	global_load_dwordx4 v[4:7], v[12:13], off offset:96
	global_load_dwordx4 v[8:11], v[12:13], off offset:80
	s_nop 0
	global_load_dwordx4 v[12:15], v[12:13], off offset:64
	s_nop 0
	global_load_dwordx4 v[20:23], v[18:19], off offset:528
	global_load_dwordx4 v[44:47], v[18:19], off offset:512
	s_nop 0
	global_load_dwordx4 v[16:19], v[40:41], off offset:16
	s_nop 0
	global_load_dwordx4 v[40:43], v[40:41], off
	global_load_dwordx4 v[100:103], v52, s[4:5]
	global_load_dwordx4 v[104:107], v52, s[4:5] offset:16
	global_load_dwordx4 v[108:111], v52, s[4:5] offset:1024
	global_load_dwordx4 v[112:115], v52, s[4:5] offset:1040
	global_load_dwordx4 v[116:119], v52, s[4:5] offset:32
	global_load_dwordx4 v[120:123], v52, s[4:5] offset:48
	global_load_dwordx4 v[124:127], v52, s[4:5] offset:1056
	global_load_dwordx4 v[128:131], v52, s[4:5] offset:1072
	s_waitcnt lgkmcnt(0)
	s_barrier
	s_sub_i32 s1, s1, s36
	s_mul_i32 s45, s42, 0x84
	s_mov_b32 s44, 0
	s_bfe_u32 s2, s37, 0x20006
	s_lshl_b32 s3, s2, 5
	s_add_i32 s10, s43, s3
	s_addk_i32 s10, 0x2000
	v_mul_u32_u24_e32 v63, 0xc0, v83
	v_add_u32_e32 v61, s10, v63
	v_mov_b32_e32 v60, s46
	v_lshlrev_b32_e32 v63, 7, v83
	v_add_u32_e32 v62, s3, v63
	s_lshl_b32 s4, s47, 7
	s_add_i32 s4, s4, s36
	s_add_i32 s4, s4, -4
	s_lshl_b32 s4, s4, 15
	s_add_u32 s4, s19, s4
	s_addc_u32 s5, s20, 0
	s_mov_b32 s47, 0x42ac0000
	v_cmp_eq_u32_e64 s[16:17], 0, v83
	s_waitcnt vmcnt(0)
	v_lshlrev_b32_e32 v202, 16, v44
	v_and_b32_e32 v203, 0xffff0000, v44
	v_lshlrev_b32_e32 v204, 16, v45
	v_and_b32_e32 v205, 0xffff0000, v45
	v_lshlrev_b32_e32 v206, 16, v46
	v_and_b32_e32 v207, 0xffff0000, v46
	v_lshlrev_b32_e32 v208, 16, v47
	v_and_b32_e32 v209, 0xffff0000, v47
	v_lshlrev_b32_e32 v210, 16, v40
	v_and_b32_e32 v211, 0xffff0000, v40
	v_lshlrev_b32_e32 v212, 16, v41
	v_and_b32_e32 v213, 0xffff0000, v41
	v_lshlrev_b32_e32 v214, 16, v42
	v_and_b32_e32 v215, 0xffff0000, v42
	v_lshlrev_b32_e32 v216, 16, v43
	v_and_b32_e32 v217, 0xffff0000, v43
	ds_read_b128 v[132:135], v60
	ds_read_b128 v[136:139], v60 offset:16
	ds_read_b128 v[140:143], v60 offset:256
	ds_read_b128 v[144:147], v60 offset:272
	ds_read_b128 v[148:151], v60 offset:512
	ds_read_b128 v[152:155], v60 offset:528
	ds_read_b128 v[156:159], v60 offset:768
	ds_read_b128 v[160:163], v60 offset:784
	ds_read_b128 v[164:167], v60 offset:1024
	ds_read_b128 v[168:171], v60 offset:1040
	ds_read_b128 v[172:175], v60 offset:1280
	ds_read_b128 v[176:179], v60 offset:1296
	v_pk_mul_f32 v[84:85], v[100:101], s[12:13] op_sel_hi:[1,0]
	v_pk_mul_f32 v[86:87], v[102:103], s[12:13] op_sel_hi:[1,0]
	v_pk_mul_f32 v[88:89], v[104:105], s[12:13] op_sel_hi:[1,0]
	v_pk_mul_f32 v[90:91], v[106:107], s[12:13] op_sel_hi:[1,0]
	s_waitcnt lgkmcnt(11)
	v_pk_fma_f32 v[84:85], v[36:37], v[132:133], v[84:85] op_sel_hi:[0,1,1]
	v_pk_fma_f32 v[86:87], v[36:37], v[134:135], v[86:87] op_sel_hi:[0,1,1]
	ds_read_b128 v[132:135], v60 offset:1536
	s_waitcnt lgkmcnt(11)
	v_pk_fma_f32 v[88:89], v[36:37], v[136:137], v[88:89] op_sel_hi:[0,1,1]
	v_pk_fma_f32 v[90:91], v[36:37], v[138:139], v[90:91] op_sel_hi:[0,1,1]
	ds_read_b128 v[136:139], v60 offset:1552
	s_waitcnt lgkmcnt(11)
	v_pk_fma_f32 v[84:85], v[36:37], v[140:141], v[84:85] op_sel:[1,0,0]
	v_pk_fma_f32 v[86:87], v[36:37], v[142:143], v[86:87] op_sel:[1,0,0]
	ds_read_b128 v[140:143], v60 offset:1792
	s_waitcnt lgkmcnt(11)
	v_pk_fma_f32 v[88:89], v[36:37], v[144:145], v[88:89] op_sel:[1,0,0]
	v_pk_fma_f32 v[90:91], v[36:37], v[146:147], v[90:91] op_sel:[1,0,0]
	ds_read_b128 v[144:147], v60 offset:1808
	s_waitcnt lgkmcnt(11)
	v_pk_fma_f32 v[84:85], v[38:39], v[148:149], v[84:85] op_sel_hi:[0,1,1]
	v_pk_fma_f32 v[86:87], v[38:39], v[150:151], v[86:87] op_sel_hi:[0,1,1]
	ds_read_b128 v[148:151], v60 offset:2048
	s_waitcnt lgkmcnt(11)
	v_pk_fma_f32 v[88:89], v[38:39], v[152:153], v[88:89] op_sel_hi:[0,1,1]
	v_pk_fma_f32 v[90:91], v[38:39], v[154:155], v[90:91] op_sel_hi:[0,1,1]
	ds_read_b128 v[152:155], v60 offset:2064
	s_waitcnt lgkmcnt(11)
	v_pk_fma_f32 v[84:85], v[38:39], v[156:157], v[84:85] op_sel:[1,0,0]
	v_pk_fma_f32 v[86:87], v[38:39], v[158:159], v[86:87] op_sel:[1,0,0]
	ds_read_b128 v[156:159], v60 offset:2304
	s_waitcnt lgkmcnt(11)
	v_pk_fma_f32 v[88:89], v[38:39], v[160:161], v[88:89] op_sel:[1,0,0]
	v_pk_fma_f32 v[90:91], v[38:39], v[162:163], v[90:91] op_sel:[1,0,0]
	ds_read_b128 v[160:163], v60 offset:2320
	s_waitcnt lgkmcnt(11)
	v_pk_fma_f32 v[84:85], v[32:33], v[164:165], v[84:85] op_sel_hi:[0,1,1]
	v_pk_fma_f32 v[86:87], v[32:33], v[166:167], v[86:87] op_sel_hi:[0,1,1]
	ds_read_b128 v[164:167], v60 offset:2560
	s_waitcnt lgkmcnt(11)
	v_pk_fma_f32 v[88:89], v[32:33], v[168:169], v[88:89] op_sel_hi:[0,1,1]
	v_pk_fma_f32 v[90:91], v[32:33], v[170:171], v[90:91] op_sel_hi:[0,1,1]
	ds_read_b128 v[168:171], v60 offset:2576
	s_waitcnt lgkmcnt(11)
	v_pk_fma_f32 v[84:85], v[32:33], v[172:173], v[84:85] op_sel:[1,0,0]
	v_pk_fma_f32 v[86:87], v[32:33], v[174:175], v[86:87] op_sel:[1,0,0]
	ds_read_b128 v[172:175], v60 offset:2816
	s_waitcnt lgkmcnt(11)
	v_pk_fma_f32 v[88:89], v[32:33], v[176:177], v[88:89] op_sel:[1,0,0]
	v_pk_fma_f32 v[90:91], v[32:33], v[178:179], v[90:91] op_sel:[1,0,0]
	ds_read_b128 v[176:179], v60 offset:2832
	s_waitcnt lgkmcnt(11)
	v_pk_fma_f32 v[84:85], v[34:35], v[132:133], v[84:85] op_sel_hi:[0,1,1]
	v_pk_fma_f32 v[86:87], v[34:35], v[134:135], v[86:87] op_sel_hi:[0,1,1]
	ds_read_b128 v[132:135], v60 offset:3072
	s_waitcnt lgkmcnt(11)
	v_pk_fma_f32 v[88:89], v[34:35], v[136:137], v[88:89] op_sel_hi:[0,1,1]
	v_pk_fma_f32 v[90:91], v[34:35], v[138:139], v[90:91] op_sel_hi:[0,1,1]
	ds_read_b128 v[136:139], v60 offset:3088
	s_waitcnt lgkmcnt(11)
	v_pk_fma_f32 v[84:85], v[34:35], v[140:141], v[84:85] op_sel:[1,0,0]
	v_pk_fma_f32 v[86:87], v[34:35], v[142:143], v[86:87] op_sel:[1,0,0]
	ds_read_b128 v[140:143], v60 offset:3328
	s_waitcnt lgkmcnt(11)
	v_pk_fma_f32 v[88:89], v[34:35], v[144:145], v[88:89] op_sel:[1,0,0]
	v_pk_fma_f32 v[90:91], v[34:35], v[146:147], v[90:91] op_sel:[1,0,0]
	ds_read_b128 v[144:147], v60 offset:3344
	s_waitcnt lgkmcnt(11)
	v_pk_fma_f32 v[84:85], v[28:29], v[148:149], v[84:85] op_sel_hi:[0,1,1]
	v_pk_fma_f32 v[86:87], v[28:29], v[150:151], v[86:87] op_sel_hi:[0,1,1]
	ds_read_b128 v[148:151], v60 offset:3584
	s_waitcnt lgkmcnt(11)
	v_pk_fma_f32 v[88:89], v[28:29], v[152:153], v[88:89] op_sel_hi:[0,1,1]
	v_pk_fma_f32 v[90:91], v[28:29], v[154:155], v[90:91] op_sel_hi:[0,1,1]
	ds_read_b128 v[152:155], v60 offset:3600
	s_waitcnt lgkmcnt(11)
	v_pk_fma_f32 v[84:85], v[28:29], v[156:157], v[84:85] op_sel:[1,0,0]
	v_pk_fma_f32 v[86:87], v[28:29], v[158:159], v[86:87] op_sel:[1,0,0]
	ds_read_b128 v[156:159], v60 offset:3840
	s_waitcnt lgkmcnt(11)
	v_pk_fma_f32 v[88:89], v[28:29], v[160:161], v[88:89] op_sel:[1,0,0]
	v_pk_fma_f32 v[90:91], v[28:29], v[162:163], v[90:91] op_sel:[1,0,0]
	ds_read_b128 v[160:163], v60 offset:3856
	s_waitcnt lgkmcnt(11)
	v_pk_fma_f32 v[84:85], v[30:31], v[164:165], v[84:85] op_sel_hi:[0,1,1]
	v_pk_fma_f32 v[86:87], v[30:31], v[166:167], v[86:87] op_sel_hi:[0,1,1]
	s_waitcnt lgkmcnt(10)
	v_pk_fma_f32 v[88:89], v[30:31], v[168:169], v[88:89] op_sel_hi:[0,1,1]
	v_pk_fma_f32 v[90:91], v[30:31], v[170:171], v[90:91] op_sel_hi:[0,1,1]
	s_waitcnt lgkmcnt(9)
	v_pk_fma_f32 v[84:85], v[30:31], v[172:173], v[84:85] op_sel:[1,0,0]
	v_pk_fma_f32 v[86:87], v[30:31], v[174:175], v[86:87] op_sel:[1,0,0]
	s_waitcnt lgkmcnt(8)
	v_pk_fma_f32 v[88:89], v[30:31], v[176:177], v[88:89] op_sel:[1,0,0]
	v_pk_fma_f32 v[90:91], v[30:31], v[178:179], v[90:91] op_sel:[1,0,0]
	s_waitcnt lgkmcnt(7)
	v_pk_fma_f32 v[84:85], v[24:25], v[132:133], v[84:85] op_sel_hi:[0,1,1]
	v_pk_fma_f32 v[86:87], v[24:25], v[134:135], v[86:87] op_sel_hi:[0,1,1]
	s_waitcnt lgkmcnt(6)
	v_pk_fma_f32 v[88:89], v[24:25], v[136:137], v[88:89] op_sel_hi:[0,1,1]
	v_pk_fma_f32 v[90:91], v[24:25], v[138:139], v[90:91] op_sel_hi:[0,1,1]
	s_waitcnt lgkmcnt(5)
	v_pk_fma_f32 v[84:85], v[24:25], v[140:141], v[84:85] op_sel:[1,0,0]
	v_pk_fma_f32 v[86:87], v[24:25], v[142:143], v[86:87] op_sel:[1,0,0]
	s_waitcnt lgkmcnt(4)
	v_pk_fma_f32 v[88:89], v[24:25], v[144:145], v[88:89] op_sel:[1,0,0]
	v_pk_fma_f32 v[90:91], v[24:25], v[146:147], v[90:91] op_sel:[1,0,0]
	s_waitcnt lgkmcnt(3)
	v_pk_fma_f32 v[84:85], v[26:27], v[148:149], v[84:85] op_sel_hi:[0,1,1]
	v_pk_fma_f32 v[86:87], v[26:27], v[150:151], v[86:87] op_sel_hi:[0,1,1]
	s_waitcnt lgkmcnt(2)
	v_pk_fma_f32 v[88:89], v[26:27], v[152:153], v[88:89] op_sel_hi:[0,1,1]
	v_pk_fma_f32 v[90:91], v[26:27], v[154:155], v[90:91] op_sel_hi:[0,1,1]
	s_waitcnt lgkmcnt(1)
	v_pk_fma_f32 v[84:85], v[26:27], v[156:157], v[84:85] op_sel:[1,0,0]
	v_pk_fma_f32 v[86:87], v[26:27], v[158:159], v[86:87] op_sel:[1,0,0]
	s_waitcnt lgkmcnt(0)
	v_pk_fma_f32 v[88:89], v[26:27], v[160:161], v[88:89] op_sel:[1,0,0]
	v_pk_fma_f32 v[90:91], v[26:27], v[162:163], v[90:91] op_sel:[1,0,0]
	v_exp_f32_e64 v242, -|v84|
	v_exp_f32_e64 v243, -|v85|
	v_exp_f32_e64 v244, -|v86|
	v_exp_f32_e64 v245, -|v87|
	v_exp_f32_e64 v246, -|v88|
	v_exp_f32_e64 v247, -|v89|
	v_exp_f32_e64 v248, -|v90|
	v_exp_f32_e64 v249, -|v91|
	v_add_f32_e32 v242, 1.0, v242
	v_add_f32_e32 v243, 1.0, v243
	v_add_f32_e32 v244, 1.0, v244
	v_add_f32_e32 v245, 1.0, v245
	v_add_f32_e32 v246, 1.0, v246
	v_add_f32_e32 v247, 1.0, v247
	v_add_f32_e32 v248, 1.0, v248
	v_add_f32_e32 v249, 1.0, v249
	v_log_f32_e32 v242, v242
	v_log_f32_e32 v243, v243
	v_log_f32_e32 v244, v244
	v_log_f32_e32 v245, v245
	v_log_f32_e32 v246, v246
	v_log_f32_e32 v247, v247
	v_log_f32_e32 v248, v248
	v_log_f32_e32 v249, v249
	v_min_f32_e32 v92, 0, v84
	v_min_f32_e32 v93, 0, v85
	v_min_f32_e32 v94, 0, v86
	v_min_f32_e32 v95, 0, v87
	v_min_f32_e32 v96, 0, v88
	v_min_f32_e32 v97, 0, v89
	v_min_f32_e32 v98, 0, v90
	v_min_f32_e32 v99, 0, v91
	v_sub_f32_e32 v92, v92, v242
	v_sub_f32_e32 v93, v93, v243
	v_sub_f32_e32 v94, v94, v244
	v_sub_f32_e32 v95, v95, v245
	v_sub_f32_e32 v96, v96, v246
	v_sub_f32_e32 v97, v97, v247
	v_sub_f32_e32 v98, v98, v248
	v_sub_f32_e32 v99, v99, v249
	v_mul_f32_e32 v92, 0x3d800000, v92
	v_mul_f32_e32 v93, 0x3d800000, v93
	v_mul_f32_e32 v94, 0x3d800000, v94
	v_mul_f32_e32 v95, 0x3d800000, v95
	v_mul_f32_e32 v96, 0x3d800000, v96
	v_mul_f32_e32 v97, 0x3d800000, v97
	v_mul_f32_e32 v98, 0x3d800000, v98
	v_mul_f32_e32 v99, 0x3d800000, v99
	v_add_f32_dpp v180, v92, v92 row_shr:1 row_mask:0xf bank_mask:0xf bound_ctrl:1
	v_add_f32_dpp v181, v93, v93 row_shr:1 row_mask:0xf bank_mask:0xf bound_ctrl:1
	v_add_f32_dpp v182, v94, v94 row_shr:1 row_mask:0xf bank_mask:0xf bound_ctrl:1
	v_add_f32_dpp v183, v95, v95 row_shr:1 row_mask:0xf bank_mask:0xf bound_ctrl:1
	v_add_f32_dpp v184, v96, v96 row_shr:1 row_mask:0xf bank_mask:0xf bound_ctrl:1
	v_add_f32_dpp v185, v97, v97 row_shr:1 row_mask:0xf bank_mask:0xf bound_ctrl:1
	v_add_f32_dpp v186, v98, v98 row_shr:1 row_mask:0xf bank_mask:0xf bound_ctrl:1
	v_add_f32_dpp v187, v99, v99 row_shr:1 row_mask:0xf bank_mask:0xf bound_ctrl:1
	v_add_f32_dpp v180, v180, v180 row_shr:2 row_mask:0xf bank_mask:0xf bound_ctrl:1
	v_add_f32_dpp v181, v181, v181 row_shr:2 row_mask:0xf bank_mask:0xf bound_ctrl:1
	v_add_f32_dpp v182, v182, v182 row_shr:2 row_mask:0xf bank_mask:0xf bound_ctrl:1
	v_add_f32_dpp v183, v183, v183 row_shr:2 row_mask:0xf bank_mask:0xf bound_ctrl:1
	v_add_f32_dpp v184, v184, v184 row_shr:2 row_mask:0xf bank_mask:0xf bound_ctrl:1
	v_add_f32_dpp v185, v185, v185 row_shr:2 row_mask:0xf bank_mask:0xf bound_ctrl:1
	v_add_f32_dpp v186, v186, v186 row_shr:2 row_mask:0xf bank_mask:0xf bound_ctrl:1
	v_add_f32_dpp v187, v187, v187 row_shr:2 row_mask:0xf bank_mask:0xf bound_ctrl:1
	v_add_f32_dpp v180, v180, v180 row_shr:4 row_mask:0xf bank_mask:0xf bound_ctrl:1
	v_add_f32_dpp v181, v181, v181 row_shr:4 row_mask:0xf bank_mask:0xf bound_ctrl:1
	v_add_f32_dpp v182, v182, v182 row_shr:4 row_mask:0xf bank_mask:0xf bound_ctrl:1
	v_add_f32_dpp v183, v183, v183 row_shr:4 row_mask:0xf bank_mask:0xf bound_ctrl:1
	v_add_f32_dpp v184, v184, v184 row_shr:4 row_mask:0xf bank_mask:0xf bound_ctrl:1
	v_add_f32_dpp v185, v185, v185 row_shr:4 row_mask:0xf bank_mask:0xf bound_ctrl:1
	v_add_f32_dpp v186, v186, v186 row_shr:4 row_mask:0xf bank_mask:0xf bound_ctrl:1
	v_add_f32_dpp v187, v187, v187 row_shr:4 row_mask:0xf bank_mask:0xf bound_ctrl:1
	v_add_f32_dpp v180, v180, v180 row_shr:8 row_mask:0xf bank_mask:0xf bound_ctrl:1
	v_add_f32_dpp v181, v181, v181 row_shr:8 row_mask:0xf bank_mask:0xf bound_ctrl:1
	v_add_f32_dpp v182, v182, v182 row_shr:8 row_mask:0xf bank_mask:0xf bound_ctrl:1
	v_add_f32_dpp v183, v183, v183 row_shr:8 row_mask:0xf bank_mask:0xf bound_ctrl:1
	v_add_f32_dpp v184, v184, v184 row_shr:8 row_mask:0xf bank_mask:0xf bound_ctrl:1
	v_add_f32_dpp v185, v185, v185 row_shr:8 row_mask:0xf bank_mask:0xf bound_ctrl:1
	v_add_f32_dpp v186, v186, v186 row_shr:8 row_mask:0xf bank_mask:0xf bound_ctrl:1
	v_add_f32_dpp v187, v187, v187 row_shr:8 row_mask:0xf bank_mask:0xf bound_ctrl:1
	v_add_f32_dpp v180, v180, v180 row_bcast:15 row_mask:0xa bank_mask:0xf
	v_add_f32_dpp v181, v181, v181 row_bcast:15 row_mask:0xa bank_mask:0xf
	v_add_f32_dpp v182, v182, v182 row_bcast:15 row_mask:0xa bank_mask:0xf
	v_add_f32_dpp v183, v183, v183 row_bcast:15 row_mask:0xa bank_mask:0xf
	v_add_f32_dpp v184, v184, v184 row_bcast:15 row_mask:0xa bank_mask:0xf
	v_add_f32_dpp v185, v185, v185 row_bcast:15 row_mask:0xa bank_mask:0xf
	v_add_f32_dpp v186, v186, v186 row_bcast:15 row_mask:0xa bank_mask:0xf
	v_add_f32_dpp v187, v187, v187 row_bcast:15 row_mask:0xa bank_mask:0xf
	v_add_f32_dpp v180, v180, v180 row_bcast:31 row_mask:0xc bank_mask:0xf
	v_add_f32_dpp v181, v181, v181 row_bcast:31 row_mask:0xc bank_mask:0xf
	v_add_f32_dpp v182, v182, v182 row_bcast:31 row_mask:0xc bank_mask:0xf
	v_add_f32_dpp v183, v183, v183 row_bcast:31 row_mask:0xc bank_mask:0xf
	v_add_f32_dpp v184, v184, v184 row_bcast:31 row_mask:0xc bank_mask:0xf
	v_add_f32_dpp v185, v185, v185 row_bcast:31 row_mask:0xc bank_mask:0xf
	v_add_f32_dpp v186, v186, v186 row_bcast:31 row_mask:0xc bank_mask:0xf
	v_add_f32_dpp v187, v187, v187 row_bcast:31 row_mask:0xc bank_mask:0xf
	v_readlane_b32 s0, v180, 63
	v_readlane_b32 s10, v181, 63
	v_readlane_b32 s14, v182, 63
	v_readlane_b32 s15, v183, 63
	v_exp_f32_e32 v234, s0
	v_exp_f32_e32 v235, s10
	v_exp_f32_e32 v236, s14
	v_exp_f32_e32 v237, s15
	v_readlane_b32 s0, v184, 63
	v_readlane_b32 s10, v185, 63
	v_readlane_b32 s14, v186, 63
	v_readlane_b32 s15, v187, 63
	v_exp_f32_e32 v238, s0
	v_exp_f32_e32 v239, s10
	v_exp_f32_e32 v240, s14
	v_exp_f32_e32 v241, s15
	v_min_f32_e64 v242, -v180, s47
	v_min_f32_e64 v243, -v181, s47
	v_min_f32_e64 v244, -v182, s47
	v_min_f32_e64 v245, -v183, s47
	v_min_f32_e64 v246, -v184, s47
	v_min_f32_e64 v247, -v185, s47
	v_min_f32_e64 v248, -v186, s47
	v_min_f32_e64 v249, -v187, s47
	v_exp_f32_e32 v226, v242
	v_exp_f32_e32 v227, v243
	v_exp_f32_e32 v228, v244
	v_exp_f32_e32 v229, v245
	v_exp_f32_e32 v230, v246
	v_exp_f32_e32 v231, v247
	v_exp_f32_e32 v232, v248
	v_exp_f32_e32 v233, v249
	v_exp_f32_e32 v218, v180
	v_exp_f32_e32 v219, v181
	v_exp_f32_e32 v220, v182
	v_exp_f32_e32 v221, v183
	v_exp_f32_e32 v222, v184
	v_exp_f32_e32 v223, v185
	v_exp_f32_e32 v224, v186
	v_exp_f32_e32 v225, v187
	v_pk_mul_f32 v[242:243], v[202:203], v[226:227]
	v_pk_mul_f32 v[244:245], v[204:205], v[228:229]
	v_pk_mul_f32 v[246:247], v[206:207], v[230:231]
	v_pk_mul_f32 v[248:249], v[208:209], v[232:233]
	v_pk_mul_f32 v[92:93], v[242:243], v[234:235]
	v_pk_mul_f32 v[94:95], v[244:245], v[236:237]
	v_pk_mul_f32 v[96:97], v[246:247], v[238:239]
	v_pk_mul_f32 v[98:99], v[248:249], v[240:241]
	v_cvt_pk_bf16_f32 v48, v92, v93
	v_cvt_pk_bf16_f32 v49, v94, v95
	v_cvt_pk_bf16_f32 v50, v96, v97
	v_cvt_pk_bf16_f32 v51, v98, v99
	ds_write_b128 v61, v[48:51] offset:0
	s_add_i32 s48, s45, s36
	s_lshl_b32 s48, s48, 8
	s_add_u32 s48, s38, s48
	s_addc_u32 s49, s39, 0
	s_mov_b64 exec, s[16:17]
	global_store_dwordx4 v65, v[234:237], s[48:49]
	global_store_dwordx4 v65, v[238:241], s[48:49] offset:16
	s_mov_b64 exec, -1
	s_cmp_gt_i32 s36, 3
	s_cbranch_scc0 .Lgla_noq_0
	v_pk_mul_f32 v[218:219], v[210:211], v[218:219]
	v_pk_mul_f32 v[220:221], v[212:213], v[220:221]
	v_pk_mul_f32 v[222:223], v[214:215], v[222:223]
	v_pk_mul_f32 v[224:225], v[216:217], v[224:225]
	v_cvt_pk_bf16_f32 v52, v218, v219
	v_cvt_pk_bf16_f32 v53, v220, v221
	v_cvt_pk_bf16_f32 v54, v222, v223
	v_cvt_pk_bf16_f32 v55, v224, v225
	v_cvt_pk_bf16_f32 v56, v242, v243
	v_cvt_pk_bf16_f32 v57, v244, v245
	v_cvt_pk_bf16_f32 v58, v246, v247
	v_cvt_pk_bf16_f32 v59, v248, v249
	s_add_u32 s48, s4, 0x0
	s_addc_u32 s49, s5, 0
	global_store_dwordx4 v62, v[52:55], s[48:49]
	s_add_u32 s48, s4, 0x2000
	s_addc_u32 s49, s5, 0
	global_store_dwordx4 v62, v[56:59], s[48:49]
.Lgla_noq_0:
	ds_read_b128 v[132:135], v60 offset:4096
	ds_read_b128 v[136:139], v60 offset:4112
	ds_read_b128 v[140:143], v60 offset:4352
	ds_read_b128 v[144:147], v60 offset:4368
	ds_read_b128 v[148:151], v60 offset:4608
	ds_read_b128 v[152:155], v60 offset:4624
	ds_read_b128 v[156:159], v60 offset:4864
	ds_read_b128 v[160:163], v60 offset:4880
	ds_read_b128 v[164:167], v60 offset:5120
	ds_read_b128 v[168:171], v60 offset:5136
	ds_read_b128 v[172:175], v60 offset:5376
	ds_read_b128 v[176:179], v60 offset:5392
	v_pk_mul_f32 v[84:85], v[108:109], s[12:13] op_sel_hi:[1,0]
	v_pk_mul_f32 v[86:87], v[110:111], s[12:13] op_sel_hi:[1,0]
	v_pk_mul_f32 v[88:89], v[112:113], s[12:13] op_sel_hi:[1,0]
	v_pk_mul_f32 v[90:91], v[114:115], s[12:13] op_sel_hi:[1,0]
	s_waitcnt lgkmcnt(11)
	v_pk_fma_f32 v[84:85], v[12:13], v[132:133], v[84:85] op_sel_hi:[0,1,1]
	v_pk_fma_f32 v[86:87], v[12:13], v[134:135], v[86:87] op_sel_hi:[0,1,1]
	ds_read_b128 v[132:135], v60 offset:5632
	s_waitcnt lgkmcnt(11)
	v_pk_fma_f32 v[88:89], v[12:13], v[136:137], v[88:89] op_sel_hi:[0,1,1]
	v_pk_fma_f32 v[90:91], v[12:13], v[138:139], v[90:91] op_sel_hi:[0,1,1]
	ds_read_b128 v[136:139], v60 offset:5648
	s_waitcnt lgkmcnt(11)
	v_pk_fma_f32 v[84:85], v[12:13], v[140:141], v[84:85] op_sel:[1,0,0]
	v_pk_fma_f32 v[86:87], v[12:13], v[142:143], v[86:87] op_sel:[1,0,0]
	ds_read_b128 v[140:143], v60 offset:5888
	s_waitcnt lgkmcnt(11)
	v_pk_fma_f32 v[88:89], v[12:13], v[144:145], v[88:89] op_sel:[1,0,0]
	v_pk_fma_f32 v[90:91], v[12:13], v[146:147], v[90:91] op_sel:[1,0,0]
	ds_read_b128 v[144:147], v60 offset:5904
	s_waitcnt lgkmcnt(11)
	v_pk_fma_f32 v[84:85], v[14:15], v[148:149], v[84:85] op_sel_hi:[0,1,1]
	v_pk_fma_f32 v[86:87], v[14:15], v[150:151], v[86:87] op_sel_hi:[0,1,1]
	ds_read_b128 v[148:151], v60 offset:6144
	s_waitcnt lgkmcnt(11)
	v_pk_fma_f32 v[88:89], v[14:15], v[152:153], v[88:89] op_sel_hi:[0,1,1]
	v_pk_fma_f32 v[90:91], v[14:15], v[154:155], v[90:91] op_sel_hi:[0,1,1]
	ds_read_b128 v[152:155], v60 offset:6160
	s_waitcnt lgkmcnt(11)
	v_pk_fma_f32 v[84:85], v[14:15], v[156:157], v[84:85] op_sel:[1,0,0]
	v_pk_fma_f32 v[86:87], v[14:15], v[158:159], v[86:87] op_sel:[1,0,0]
	ds_read_b128 v[156:159], v60 offset:6400
	s_waitcnt lgkmcnt(11)
	v_pk_fma_f32 v[88:89], v[14:15], v[160:161], v[88:89] op_sel:[1,0,0]
	v_pk_fma_f32 v[90:91], v[14:15], v[162:163], v[90:91] op_sel:[1,0,0]
	ds_read_b128 v[160:163], v60 offset:6416
	s_waitcnt lgkmcnt(11)
	v_pk_fma_f32 v[84:85], v[8:9], v[164:165], v[84:85] op_sel_hi:[0,1,1]
	v_pk_fma_f32 v[86:87], v[8:9], v[166:167], v[86:87] op_sel_hi:[0,1,1]
	ds_read_b128 v[164:167], v60 offset:6656
	s_waitcnt lgkmcnt(11)
	v_pk_fma_f32 v[88:89], v[8:9], v[168:169], v[88:89] op_sel_hi:[0,1,1]
	v_pk_fma_f32 v[90:91], v[8:9], v[170:171], v[90:91] op_sel_hi:[0,1,1]
	ds_read_b128 v[168:171], v60 offset:6672
	s_waitcnt lgkmcnt(11)
	v_pk_fma_f32 v[84:85], v[8:9], v[172:173], v[84:85] op_sel:[1,0,0]
	v_pk_fma_f32 v[86:87], v[8:9], v[174:175], v[86:87] op_sel:[1,0,0]
	ds_read_b128 v[172:175], v60 offset:6912
	s_waitcnt lgkmcnt(11)
	v_pk_fma_f32 v[88:89], v[8:9], v[176:177], v[88:89] op_sel:[1,0,0]
	v_pk_fma_f32 v[90:91], v[8:9], v[178:179], v[90:91] op_sel:[1,0,0]
	ds_read_b128 v[176:179], v60 offset:6928
	s_waitcnt lgkmcnt(11)
	v_pk_fma_f32 v[84:85], v[10:11], v[132:133], v[84:85] op_sel_hi:[0,1,1]
	v_pk_fma_f32 v[86:87], v[10:11], v[134:135], v[86:87] op_sel_hi:[0,1,1]
	ds_read_b128 v[132:135], v60 offset:7168
	s_waitcnt lgkmcnt(11)
	v_pk_fma_f32 v[88:89], v[10:11], v[136:137], v[88:89] op_sel_hi:[0,1,1]
	v_pk_fma_f32 v[90:91], v[10:11], v[138:139], v[90:91] op_sel_hi:[0,1,1]
	ds_read_b128 v[136:139], v60 offset:7184
	s_waitcnt lgkmcnt(11)
	v_pk_fma_f32 v[84:85], v[10:11], v[140:141], v[84:85] op_sel:[1,0,0]
	v_pk_fma_f32 v[86:87], v[10:11], v[142:143], v[86:87] op_sel:[1,0,0]
	ds_read_b128 v[140:143], v60 offset:7424
	s_waitcnt lgkmcnt(11)
	v_pk_fma_f32 v[88:89], v[10:11], v[144:145], v[88:89] op_sel:[1,0,0]
	v_pk_fma_f32 v[90:91], v[10:11], v[146:147], v[90:91] op_sel:[1,0,0]
	ds_read_b128 v[144:147], v60 offset:7440
	s_waitcnt lgkmcnt(11)
	v_pk_fma_f32 v[84:85], v[4:5], v[148:149], v[84:85] op_sel_hi:[0,1,1]
	v_pk_fma_f32 v[86:87], v[4:5], v[150:151], v[86:87] op_sel_hi:[0,1,1]
	ds_read_b128 v[148:151], v60 offset:7680
	s_waitcnt lgkmcnt(11)
	v_pk_fma_f32 v[88:89], v[4:5], v[152:153], v[88:89] op_sel_hi:[0,1,1]
	v_pk_fma_f32 v[90:91], v[4:5], v[154:155], v[90:91] op_sel_hi:[0,1,1]
	ds_read_b128 v[152:155], v60 offset:7696
	s_waitcnt lgkmcnt(11)
	v_pk_fma_f32 v[84:85], v[4:5], v[156:157], v[84:85] op_sel:[1,0,0]
	v_pk_fma_f32 v[86:87], v[4:5], v[158:159], v[86:87] op_sel:[1,0,0]
	ds_read_b128 v[156:159], v60 offset:7936
	s_waitcnt lgkmcnt(11)
	v_pk_fma_f32 v[88:89], v[4:5], v[160:161], v[88:89] op_sel:[1,0,0]
	v_pk_fma_f32 v[90:91], v[4:5], v[162:163], v[90:91] op_sel:[1,0,0]
	ds_read_b128 v[160:163], v60 offset:7952
	s_waitcnt lgkmcnt(11)
	v_pk_fma_f32 v[84:85], v[6:7], v[164:165], v[84:85] op_sel_hi:[0,1,1]
	v_pk_fma_f32 v[86:87], v[6:7], v[166:167], v[86:87] op_sel_hi:[0,1,1]
	s_waitcnt lgkmcnt(10)
	v_pk_fma_f32 v[88:89], v[6:7], v[168:169], v[88:89] op_sel_hi:[0,1,1]
	v_pk_fma_f32 v[90:91], v[6:7], v[170:171], v[90:91] op_sel_hi:[0,1,1]
	s_waitcnt lgkmcnt(9)
	v_pk_fma_f32 v[84:85], v[6:7], v[172:173], v[84:85] op_sel:[1,0,0]
	v_pk_fma_f32 v[86:87], v[6:7], v[174:175], v[86:87] op_sel:[1,0,0]
	s_waitcnt lgkmcnt(8)
	v_pk_fma_f32 v[88:89], v[6:7], v[176:177], v[88:89] op_sel:[1,0,0]
	v_pk_fma_f32 v[90:91], v[6:7], v[178:179], v[90:91] op_sel:[1,0,0]
	s_waitcnt lgkmcnt(7)
	v_pk_fma_f32 v[84:85], v[0:1], v[132:133], v[84:85] op_sel_hi:[0,1,1]
	v_pk_fma_f32 v[86:87], v[0:1], v[134:135], v[86:87] op_sel_hi:[0,1,1]
	s_waitcnt lgkmcnt(6)
	v_pk_fma_f32 v[88:89], v[0:1], v[136:137], v[88:89] op_sel_hi:[0,1,1]
	v_pk_fma_f32 v[90:91], v[0:1], v[138:139], v[90:91] op_sel_hi:[0,1,1]
	s_waitcnt lgkmcnt(5)
	v_pk_fma_f32 v[84:85], v[0:1], v[140:141], v[84:85] op_sel:[1,0,0]
	v_pk_fma_f32 v[86:87], v[0:1], v[142:143], v[86:87] op_sel:[1,0,0]
	s_waitcnt lgkmcnt(4)
	v_pk_fma_f32 v[88:89], v[0:1], v[144:145], v[88:89] op_sel:[1,0,0]
	v_pk_fma_f32 v[90:91], v[0:1], v[146:147], v[90:91] op_sel:[1,0,0]
	s_waitcnt lgkmcnt(3)
	v_pk_fma_f32 v[84:85], v[2:3], v[148:149], v[84:85] op_sel_hi:[0,1,1]
	v_pk_fma_f32 v[86:87], v[2:3], v[150:151], v[86:87] op_sel_hi:[0,1,1]
	s_waitcnt lgkmcnt(2)
	v_pk_fma_f32 v[88:89], v[2:3], v[152:153], v[88:89] op_sel_hi:[0,1,1]
	v_pk_fma_f32 v[90:91], v[2:3], v[154:155], v[90:91] op_sel_hi:[0,1,1]
	s_waitcnt lgkmcnt(1)
	v_pk_fma_f32 v[84:85], v[2:3], v[156:157], v[84:85] op_sel:[1,0,0]
	v_pk_fma_f32 v[86:87], v[2:3], v[158:159], v[86:87] op_sel:[1,0,0]
	s_waitcnt lgkmcnt(0)
	v_pk_fma_f32 v[88:89], v[2:3], v[160:161], v[88:89] op_sel:[1,0,0]
	v_pk_fma_f32 v[90:91], v[2:3], v[162:163], v[90:91] op_sel:[1,0,0]
	v_exp_f32_e64 v242, -|v84|
	v_exp_f32_e64 v243, -|v85|
	v_exp_f32_e64 v244, -|v86|
	v_exp_f32_e64 v245, -|v87|
	v_exp_f32_e64 v246, -|v88|
	v_exp_f32_e64 v247, -|v89|
	v_exp_f32_e64 v248, -|v90|
	v_exp_f32_e64 v249, -|v91|
	v_add_f32_e32 v242, 1.0, v242
	v_add_f32_e32 v243, 1.0, v243
	v_add_f32_e32 v244, 1.0, v244
	v_add_f32_e32 v245, 1.0, v245
	v_add_f32_e32 v246, 1.0, v246
	v_add_f32_e32 v247, 1.0, v247
	v_add_f32_e32 v248, 1.0, v248
	v_add_f32_e32 v249, 1.0, v249
	v_log_f32_e32 v242, v242
	v_log_f32_e32 v243, v243
	v_log_f32_e32 v244, v244
	v_log_f32_e32 v245, v245
	v_log_f32_e32 v246, v246
	v_log_f32_e32 v247, v247
	v_log_f32_e32 v248, v248
	v_log_f32_e32 v249, v249
	v_min_f32_e32 v92, 0, v84
	v_min_f32_e32 v93, 0, v85
	v_min_f32_e32 v94, 0, v86
	v_min_f32_e32 v95, 0, v87
	v_min_f32_e32 v96, 0, v88
	v_min_f32_e32 v97, 0, v89
	v_min_f32_e32 v98, 0, v90
	v_min_f32_e32 v99, 0, v91
	v_sub_f32_e32 v92, v92, v242
	v_sub_f32_e32 v93, v93, v243
	v_sub_f32_e32 v94, v94, v244
	v_sub_f32_e32 v95, v95, v245
	v_sub_f32_e32 v96, v96, v246
	v_sub_f32_e32 v97, v97, v247
	v_sub_f32_e32 v98, v98, v248
	v_sub_f32_e32 v99, v99, v249
	v_mul_f32_e32 v92, 0x3d800000, v92
	v_mul_f32_e32 v93, 0x3d800000, v93
	v_mul_f32_e32 v94, 0x3d800000, v94
	v_mul_f32_e32 v95, 0x3d800000, v95
	v_mul_f32_e32 v96, 0x3d800000, v96
	v_mul_f32_e32 v97, 0x3d800000, v97
	v_mul_f32_e32 v98, 0x3d800000, v98
	v_mul_f32_e32 v99, 0x3d800000, v99
	v_add_f32_dpp v180, v92, v92 row_shr:1 row_mask:0xf bank_mask:0xf bound_ctrl:1
	v_add_f32_dpp v181, v93, v93 row_shr:1 row_mask:0xf bank_mask:0xf bound_ctrl:1
	v_add_f32_dpp v182, v94, v94 row_shr:1 row_mask:0xf bank_mask:0xf bound_ctrl:1
	v_add_f32_dpp v183, v95, v95 row_shr:1 row_mask:0xf bank_mask:0xf bound_ctrl:1
	v_add_f32_dpp v184, v96, v96 row_shr:1 row_mask:0xf bank_mask:0xf bound_ctrl:1
	v_add_f32_dpp v185, v97, v97 row_shr:1 row_mask:0xf bank_mask:0xf bound_ctrl:1
	v_add_f32_dpp v186, v98, v98 row_shr:1 row_mask:0xf bank_mask:0xf bound_ctrl:1
	v_add_f32_dpp v187, v99, v99 row_shr:1 row_mask:0xf bank_mask:0xf bound_ctrl:1
	v_add_f32_dpp v180, v180, v180 row_shr:2 row_mask:0xf bank_mask:0xf bound_ctrl:1
	v_add_f32_dpp v181, v181, v181 row_shr:2 row_mask:0xf bank_mask:0xf bound_ctrl:1
	v_add_f32_dpp v182, v182, v182 row_shr:2 row_mask:0xf bank_mask:0xf bound_ctrl:1
	v_add_f32_dpp v183, v183, v183 row_shr:2 row_mask:0xf bank_mask:0xf bound_ctrl:1
	v_add_f32_dpp v184, v184, v184 row_shr:2 row_mask:0xf bank_mask:0xf bound_ctrl:1
	v_add_f32_dpp v185, v185, v185 row_shr:2 row_mask:0xf bank_mask:0xf bound_ctrl:1
	v_add_f32_dpp v186, v186, v186 row_shr:2 row_mask:0xf bank_mask:0xf bound_ctrl:1
	v_add_f32_dpp v187, v187, v187 row_shr:2 row_mask:0xf bank_mask:0xf bound_ctrl:1
	v_add_f32_dpp v180, v180, v180 row_shr:4 row_mask:0xf bank_mask:0xf bound_ctrl:1
	v_add_f32_dpp v181, v181, v181 row_shr:4 row_mask:0xf bank_mask:0xf bound_ctrl:1
	v_add_f32_dpp v182, v182, v182 row_shr:4 row_mask:0xf bank_mask:0xf bound_ctrl:1
	v_add_f32_dpp v183, v183, v183 row_shr:4 row_mask:0xf bank_mask:0xf bound_ctrl:1
	v_add_f32_dpp v184, v184, v184 row_shr:4 row_mask:0xf bank_mask:0xf bound_ctrl:1
	v_add_f32_dpp v185, v185, v185 row_shr:4 row_mask:0xf bank_mask:0xf bound_ctrl:1
	v_add_f32_dpp v186, v186, v186 row_shr:4 row_mask:0xf bank_mask:0xf bound_ctrl:1
	v_add_f32_dpp v187, v187, v187 row_shr:4 row_mask:0xf bank_mask:0xf bound_ctrl:1
	v_add_f32_dpp v180, v180, v180 row_shr:8 row_mask:0xf bank_mask:0xf bound_ctrl:1
	v_add_f32_dpp v181, v181, v181 row_shr:8 row_mask:0xf bank_mask:0xf bound_ctrl:1
	v_add_f32_dpp v182, v182, v182 row_shr:8 row_mask:0xf bank_mask:0xf bound_ctrl:1
	v_add_f32_dpp v183, v183, v183 row_shr:8 row_mask:0xf bank_mask:0xf bound_ctrl:1
	v_add_f32_dpp v184, v184, v184 row_shr:8 row_mask:0xf bank_mask:0xf bound_ctrl:1
	v_add_f32_dpp v185, v185, v185 row_shr:8 row_mask:0xf bank_mask:0xf bound_ctrl:1
	v_add_f32_dpp v186, v186, v186 row_shr:8 row_mask:0xf bank_mask:0xf bound_ctrl:1
	v_add_f32_dpp v187, v187, v187 row_shr:8 row_mask:0xf bank_mask:0xf bound_ctrl:1
	v_add_f32_dpp v180, v180, v180 row_bcast:15 row_mask:0xa bank_mask:0xf
	v_add_f32_dpp v181, v181, v181 row_bcast:15 row_mask:0xa bank_mask:0xf
	v_add_f32_dpp v182, v182, v182 row_bcast:15 row_mask:0xa bank_mask:0xf
	v_add_f32_dpp v183, v183, v183 row_bcast:15 row_mask:0xa bank_mask:0xf
	v_add_f32_dpp v184, v184, v184 row_bcast:15 row_mask:0xa bank_mask:0xf
	v_add_f32_dpp v185, v185, v185 row_bcast:15 row_mask:0xa bank_mask:0xf
	v_add_f32_dpp v186, v186, v186 row_bcast:15 row_mask:0xa bank_mask:0xf
	v_add_f32_dpp v187, v187, v187 row_bcast:15 row_mask:0xa bank_mask:0xf
	v_add_f32_dpp v180, v180, v180 row_bcast:31 row_mask:0xc bank_mask:0xf
	v_add_f32_dpp v181, v181, v181 row_bcast:31 row_mask:0xc bank_mask:0xf
	v_add_f32_dpp v182, v182, v182 row_bcast:31 row_mask:0xc bank_mask:0xf
	v_add_f32_dpp v183, v183, v183 row_bcast:31 row_mask:0xc bank_mask:0xf
	v_add_f32_dpp v184, v184, v184 row_bcast:31 row_mask:0xc bank_mask:0xf
	v_add_f32_dpp v185, v185, v185 row_bcast:31 row_mask:0xc bank_mask:0xf
	v_add_f32_dpp v186, v186, v186 row_bcast:31 row_mask:0xc bank_mask:0xf
	v_add_f32_dpp v187, v187, v187 row_bcast:31 row_mask:0xc bank_mask:0xf
	v_readlane_b32 s0, v180, 63
	v_readlane_b32 s10, v181, 63
	v_readlane_b32 s14, v182, 63
	v_readlane_b32 s15, v183, 63
	v_sub_f32_e32 v242, s0, v180
	v_sub_f32_e32 v243, s10, v181
	v_sub_f32_e32 v244, s14, v182
	v_sub_f32_e32 v245, s15, v183
	v_readlane_b32 s0, v184, 63
	v_readlane_b32 s10, v185, 63
	v_readlane_b32 s14, v186, 63
	v_readlane_b32 s15, v187, 63
	v_sub_f32_e32 v246, s0, v184
	v_sub_f32_e32 v247, s10, v185
	v_sub_f32_e32 v248, s14, v186
	v_sub_f32_e32 v249, s15, v187
	v_add_f32_e32 v180, v242, v92
	v_add_f32_e32 v181, v243, v93
	v_add_f32_e32 v182, v244, v94
	v_add_f32_e32 v183, v245, v95
	v_add_f32_e32 v184, v246, v96
	v_add_f32_e32 v185, v247, v97
	v_add_f32_e32 v186, v248, v98
	v_add_f32_e32 v187, v249, v99
	v_readlane_b32 s0, v180, 0
	v_readlane_b32 s10, v181, 0
	v_readlane_b32 s14, v182, 0
	v_readlane_b32 s15, v183, 0
	v_exp_f32_e32 v234, s0
	v_exp_f32_e32 v235, s10
	v_exp_f32_e32 v236, s14
	v_exp_f32_e32 v237, s15
	v_readlane_b32 s0, v184, 0
	v_readlane_b32 s10, v185, 0
	v_readlane_b32 s14, v186, 0
	v_readlane_b32 s15, v187, 0
	v_exp_f32_e32 v238, s0
	v_exp_f32_e32 v239, s10
	v_exp_f32_e32 v240, s14
	v_exp_f32_e32 v241, s15
	v_min_f32_e64 v242, -v180, s47
	v_min_f32_e64 v243, -v181, s47
	v_min_f32_e64 v244, -v182, s47
	v_min_f32_e64 v245, -v183, s47
	v_min_f32_e64 v246, -v184, s47
	v_min_f32_e64 v247, -v185, s47
	v_min_f32_e64 v248, -v186, s47
	v_min_f32_e64 v249, -v187, s47
	v_exp_f32_e32 v226, v242
	v_exp_f32_e32 v227, v243
	v_exp_f32_e32 v228, v244
	v_exp_f32_e32 v229, v245
	v_exp_f32_e32 v230, v246
	v_exp_f32_e32 v231, v247
	v_exp_f32_e32 v232, v248
	v_exp_f32_e32 v233, v249
	v_exp_f32_e32 v218, v180
	v_exp_f32_e32 v219, v181
	v_exp_f32_e32 v220, v182
	v_exp_f32_e32 v221, v183
	v_exp_f32_e32 v222, v184
	v_exp_f32_e32 v223, v185
	v_exp_f32_e32 v224, v186
	v_exp_f32_e32 v225, v187
	v_pk_mul_f32 v[242:243], v[202:203], v[226:227]
	v_pk_mul_f32 v[244:245], v[204:205], v[228:229]
	v_pk_mul_f32 v[246:247], v[206:207], v[230:231]
	v_pk_mul_f32 v[248:249], v[208:209], v[232:233]
	v_pk_mul_f32 v[92:93], v[242:243], v[234:235]
	v_pk_mul_f32 v[94:95], v[244:245], v[236:237]
	v_pk_mul_f32 v[96:97], v[246:247], v[238:239]
	v_pk_mul_f32 v[98:99], v[248:249], v[240:241]
	v_cvt_pk_bf16_f32 v48, v92, v93
	v_cvt_pk_bf16_f32 v49, v94, v95
	v_cvt_pk_bf16_f32 v50, v96, v97
	v_cvt_pk_bf16_f32 v51, v98, v99
	ds_write_b128 v61, v[48:51] offset:12288
	s_add_i32 s48, s45, s1
	s_addk_i32 s48, 0x84
	s_lshl_b32 s48, s48, 8
	s_add_u32 s48, s38, s48
	s_addc_u32 s49, s39, 0
	s_mov_b64 exec, s[16:17]
	global_store_dwordx4 v65, v[234:237], s[48:49]
	global_store_dwordx4 v65, v[238:241], s[48:49] offset:16
	s_mov_b64 exec, -1
	s_cmp_gt_i32 s36, 3
	s_cbranch_scc0 .Lgla_noq_1
	v_pk_mul_f32 v[218:219], v[210:211], v[218:219]
	v_pk_mul_f32 v[220:221], v[212:213], v[220:221]
	v_pk_mul_f32 v[222:223], v[214:215], v[222:223]
	v_pk_mul_f32 v[224:225], v[216:217], v[224:225]
	v_cvt_pk_bf16_f32 v52, v218, v219
	v_cvt_pk_bf16_f32 v53, v220, v221
	v_cvt_pk_bf16_f32 v54, v222, v223
	v_cvt_pk_bf16_f32 v55, v224, v225
	v_cvt_pk_bf16_f32 v56, v242, v243
	v_cvt_pk_bf16_f32 v57, v244, v245
	v_cvt_pk_bf16_f32 v58, v246, v247
	v_cvt_pk_bf16_f32 v59, v248, v249
	s_add_u32 s48, s4, 0x4000
	s_addc_u32 s49, s5, 0
	global_store_dwordx4 v62, v[52:55], s[48:49]
	s_add_u32 s48, s4, 0x6000
	s_addc_u32 s49, s5, 0
	global_store_dwordx4 v62, v[56:59], s[48:49]
.Lgla_noq_1:
	v_lshlrev_b32_e32 v202, 16, v20
	v_and_b32_e32 v203, 0xffff0000, v20
	v_lshlrev_b32_e32 v204, 16, v21
	v_and_b32_e32 v205, 0xffff0000, v21
	v_lshlrev_b32_e32 v206, 16, v22
	v_and_b32_e32 v207, 0xffff0000, v22
	v_lshlrev_b32_e32 v208, 16, v23
	v_and_b32_e32 v209, 0xffff0000, v23
	v_lshlrev_b32_e32 v210, 16, v16
	v_and_b32_e32 v211, 0xffff0000, v16
	v_lshlrev_b32_e32 v212, 16, v17
	v_and_b32_e32 v213, 0xffff0000, v17
	v_lshlrev_b32_e32 v214, 16, v18
	v_and_b32_e32 v215, 0xffff0000, v18
	v_lshlrev_b32_e32 v216, 16, v19
	v_and_b32_e32 v217, 0xffff0000, v19
	ds_read_b128 v[132:135], v60 offset:32
	ds_read_b128 v[136:139], v60 offset:48
	ds_read_b128 v[140:143], v60 offset:288
	ds_read_b128 v[144:147], v60 offset:304
	ds_read_b128 v[148:151], v60 offset:544
	ds_read_b128 v[152:155], v60 offset:560
	ds_read_b128 v[156:159], v60 offset:800
	ds_read_b128 v[160:163], v60 offset:816
	ds_read_b128 v[164:167], v60 offset:1056
	ds_read_b128 v[168:171], v60 offset:1072
	ds_read_b128 v[172:175], v60 offset:1312
	ds_read_b128 v[176:179], v60 offset:1328
	v_pk_mul_f32 v[84:85], v[116:117], s[12:13] op_sel_hi:[1,0]
	v_pk_mul_f32 v[86:87], v[118:119], s[12:13] op_sel_hi:[1,0]
	v_pk_mul_f32 v[88:89], v[120:121], s[12:13] op_sel_hi:[1,0]
	v_pk_mul_f32 v[90:91], v[122:123], s[12:13] op_sel_hi:[1,0]
	s_waitcnt lgkmcnt(11)
	v_pk_fma_f32 v[84:85], v[36:37], v[132:133], v[84:85] op_sel_hi:[0,1,1]
	v_pk_fma_f32 v[86:87], v[36:37], v[134:135], v[86:87] op_sel_hi:[0,1,1]
	ds_read_b128 v[132:135], v60 offset:1568
	s_waitcnt lgkmcnt(11)
	v_pk_fma_f32 v[88:89], v[36:37], v[136:137], v[88:89] op_sel_hi:[0,1,1]
	v_pk_fma_f32 v[90:91], v[36:37], v[138:139], v[90:91] op_sel_hi:[0,1,1]
	ds_read_b128 v[136:139], v60 offset:1584
	s_waitcnt lgkmcnt(11)
	v_pk_fma_f32 v[84:85], v[36:37], v[140:141], v[84:85] op_sel:[1,0,0]
	v_pk_fma_f32 v[86:87], v[36:37], v[142:143], v[86:87] op_sel:[1,0,0]
	ds_read_b128 v[140:143], v60 offset:1824
	s_waitcnt lgkmcnt(11)
	v_pk_fma_f32 v[88:89], v[36:37], v[144:145], v[88:89] op_sel:[1,0,0]
	v_pk_fma_f32 v[90:91], v[36:37], v[146:147], v[90:91] op_sel:[1,0,0]
	ds_read_b128 v[144:147], v60 offset:1840
	s_waitcnt lgkmcnt(11)
	v_pk_fma_f32 v[84:85], v[38:39], v[148:149], v[84:85] op_sel_hi:[0,1,1]
	v_pk_fma_f32 v[86:87], v[38:39], v[150:151], v[86:87] op_sel_hi:[0,1,1]
	ds_read_b128 v[148:151], v60 offset:2080
	s_waitcnt lgkmcnt(11)
	v_pk_fma_f32 v[88:89], v[38:39], v[152:153], v[88:89] op_sel_hi:[0,1,1]
	v_pk_fma_f32 v[90:91], v[38:39], v[154:155], v[90:91] op_sel_hi:[0,1,1]
	ds_read_b128 v[152:155], v60 offset:2096
	s_waitcnt lgkmcnt(11)
	v_pk_fma_f32 v[84:85], v[38:39], v[156:157], v[84:85] op_sel:[1,0,0]
	v_pk_fma_f32 v[86:87], v[38:39], v[158:159], v[86:87] op_sel:[1,0,0]
	ds_read_b128 v[156:159], v60 offset:2336
	s_waitcnt lgkmcnt(11)
	v_pk_fma_f32 v[88:89], v[38:39], v[160:161], v[88:89] op_sel:[1,0,0]
	v_pk_fma_f32 v[90:91], v[38:39], v[162:163], v[90:91] op_sel:[1,0,0]
	ds_read_b128 v[160:163], v60 offset:2352
	s_waitcnt lgkmcnt(11)
	v_pk_fma_f32 v[84:85], v[32:33], v[164:165], v[84:85] op_sel_hi:[0,1,1]
	v_pk_fma_f32 v[86:87], v[32:33], v[166:167], v[86:87] op_sel_hi:[0,1,1]
	ds_read_b128 v[164:167], v60 offset:2592
	s_waitcnt lgkmcnt(11)
	v_pk_fma_f32 v[88:89], v[32:33], v[168:169], v[88:89] op_sel_hi:[0,1,1]
	v_pk_fma_f32 v[90:91], v[32:33], v[170:171], v[90:91] op_sel_hi:[0,1,1]
	ds_read_b128 v[168:171], v60 offset:2608
	s_waitcnt lgkmcnt(11)
	v_pk_fma_f32 v[84:85], v[32:33], v[172:173], v[84:85] op_sel:[1,0,0]
	v_pk_fma_f32 v[86:87], v[32:33], v[174:175], v[86:87] op_sel:[1,0,0]
	ds_read_b128 v[172:175], v60 offset:2848
	s_waitcnt lgkmcnt(11)
	v_pk_fma_f32 v[88:89], v[32:33], v[176:177], v[88:89] op_sel:[1,0,0]
	v_pk_fma_f32 v[90:91], v[32:33], v[178:179], v[90:91] op_sel:[1,0,0]
	ds_read_b128 v[176:179], v60 offset:2864
	s_waitcnt lgkmcnt(11)
	v_pk_fma_f32 v[84:85], v[34:35], v[132:133], v[84:85] op_sel_hi:[0,1,1]
	v_pk_fma_f32 v[86:87], v[34:35], v[134:135], v[86:87] op_sel_hi:[0,1,1]
	ds_read_b128 v[132:135], v60 offset:3104
	s_waitcnt lgkmcnt(11)
	v_pk_fma_f32 v[88:89], v[34:35], v[136:137], v[88:89] op_sel_hi:[0,1,1]
	v_pk_fma_f32 v[90:91], v[34:35], v[138:139], v[90:91] op_sel_hi:[0,1,1]
	ds_read_b128 v[136:139], v60 offset:3120
	s_waitcnt lgkmcnt(11)
	v_pk_fma_f32 v[84:85], v[34:35], v[140:141], v[84:85] op_sel:[1,0,0]
	v_pk_fma_f32 v[86:87], v[34:35], v[142:143], v[86:87] op_sel:[1,0,0]
	ds_read_b128 v[140:143], v60 offset:3360
	s_waitcnt lgkmcnt(11)
	v_pk_fma_f32 v[88:89], v[34:35], v[144:145], v[88:89] op_sel:[1,0,0]
	v_pk_fma_f32 v[90:91], v[34:35], v[146:147], v[90:91] op_sel:[1,0,0]
	ds_read_b128 v[144:147], v60 offset:3376
	s_waitcnt lgkmcnt(11)
	v_pk_fma_f32 v[84:85], v[28:29], v[148:149], v[84:85] op_sel_hi:[0,1,1]
	v_pk_fma_f32 v[86:87], v[28:29], v[150:151], v[86:87] op_sel_hi:[0,1,1]
	ds_read_b128 v[148:151], v60 offset:3616
	s_waitcnt lgkmcnt(11)
	v_pk_fma_f32 v[88:89], v[28:29], v[152:153], v[88:89] op_sel_hi:[0,1,1]
	v_pk_fma_f32 v[90:91], v[28:29], v[154:155], v[90:91] op_sel_hi:[0,1,1]
	ds_read_b128 v[152:155], v60 offset:3632
	s_waitcnt lgkmcnt(11)
	v_pk_fma_f32 v[84:85], v[28:29], v[156:157], v[84:85] op_sel:[1,0,0]
	v_pk_fma_f32 v[86:87], v[28:29], v[158:159], v[86:87] op_sel:[1,0,0]
	ds_read_b128 v[156:159], v60 offset:3872
	s_waitcnt lgkmcnt(11)
	v_pk_fma_f32 v[88:89], v[28:29], v[160:161], v[88:89] op_sel:[1,0,0]
	v_pk_fma_f32 v[90:91], v[28:29], v[162:163], v[90:91] op_sel:[1,0,0]
	ds_read_b128 v[160:163], v60 offset:3888
	s_waitcnt lgkmcnt(11)
	v_pk_fma_f32 v[84:85], v[30:31], v[164:165], v[84:85] op_sel_hi:[0,1,1]
	v_pk_fma_f32 v[86:87], v[30:31], v[166:167], v[86:87] op_sel_hi:[0,1,1]
	s_waitcnt lgkmcnt(10)
	v_pk_fma_f32 v[88:89], v[30:31], v[168:169], v[88:89] op_sel_hi:[0,1,1]
	v_pk_fma_f32 v[90:91], v[30:31], v[170:171], v[90:91] op_sel_hi:[0,1,1]
	s_waitcnt lgkmcnt(9)
	v_pk_fma_f32 v[84:85], v[30:31], v[172:173], v[84:85] op_sel:[1,0,0]
	v_pk_fma_f32 v[86:87], v[30:31], v[174:175], v[86:87] op_sel:[1,0,0]
	s_waitcnt lgkmcnt(8)
	v_pk_fma_f32 v[88:89], v[30:31], v[176:177], v[88:89] op_sel:[1,0,0]
	v_pk_fma_f32 v[90:91], v[30:31], v[178:179], v[90:91] op_sel:[1,0,0]
	s_waitcnt lgkmcnt(7)
	v_pk_fma_f32 v[84:85], v[24:25], v[132:133], v[84:85] op_sel_hi:[0,1,1]
	v_pk_fma_f32 v[86:87], v[24:25], v[134:135], v[86:87] op_sel_hi:[0,1,1]
	s_waitcnt lgkmcnt(6)
	v_pk_fma_f32 v[88:89], v[24:25], v[136:137], v[88:89] op_sel_hi:[0,1,1]
	v_pk_fma_f32 v[90:91], v[24:25], v[138:139], v[90:91] op_sel_hi:[0,1,1]
	s_waitcnt lgkmcnt(5)
	v_pk_fma_f32 v[84:85], v[24:25], v[140:141], v[84:85] op_sel:[1,0,0]
	v_pk_fma_f32 v[86:87], v[24:25], v[142:143], v[86:87] op_sel:[1,0,0]
	s_waitcnt lgkmcnt(4)
	v_pk_fma_f32 v[88:89], v[24:25], v[144:145], v[88:89] op_sel:[1,0,0]
	v_pk_fma_f32 v[90:91], v[24:25], v[146:147], v[90:91] op_sel:[1,0,0]
	s_waitcnt lgkmcnt(3)
	v_pk_fma_f32 v[84:85], v[26:27], v[148:149], v[84:85] op_sel_hi:[0,1,1]
	v_pk_fma_f32 v[86:87], v[26:27], v[150:151], v[86:87] op_sel_hi:[0,1,1]
	s_waitcnt lgkmcnt(2)
	v_pk_fma_f32 v[88:89], v[26:27], v[152:153], v[88:89] op_sel_hi:[0,1,1]
	v_pk_fma_f32 v[90:91], v[26:27], v[154:155], v[90:91] op_sel_hi:[0,1,1]
	s_waitcnt lgkmcnt(1)
	v_pk_fma_f32 v[84:85], v[26:27], v[156:157], v[84:85] op_sel:[1,0,0]
	v_pk_fma_f32 v[86:87], v[26:27], v[158:159], v[86:87] op_sel:[1,0,0]
	s_waitcnt lgkmcnt(0)
	v_pk_fma_f32 v[88:89], v[26:27], v[160:161], v[88:89] op_sel:[1,0,0]
	v_pk_fma_f32 v[90:91], v[26:27], v[162:163], v[90:91] op_sel:[1,0,0]
	v_exp_f32_e64 v242, -|v84|
	v_exp_f32_e64 v243, -|v85|
	v_exp_f32_e64 v244, -|v86|
	v_exp_f32_e64 v245, -|v87|
	v_exp_f32_e64 v246, -|v88|
	v_exp_f32_e64 v247, -|v89|
	v_exp_f32_e64 v248, -|v90|
	v_exp_f32_e64 v249, -|v91|
	v_add_f32_e32 v242, 1.0, v242
	v_add_f32_e32 v243, 1.0, v243
	v_add_f32_e32 v244, 1.0, v244
	v_add_f32_e32 v245, 1.0, v245
	v_add_f32_e32 v246, 1.0, v246
	v_add_f32_e32 v247, 1.0, v247
	v_add_f32_e32 v248, 1.0, v248
	v_add_f32_e32 v249, 1.0, v249
	v_log_f32_e32 v242, v242
	v_log_f32_e32 v243, v243
	v_log_f32_e32 v244, v244
	v_log_f32_e32 v245, v245
	v_log_f32_e32 v246, v246
	v_log_f32_e32 v247, v247
	v_log_f32_e32 v248, v248
	v_log_f32_e32 v249, v249
	v_min_f32_e32 v92, 0, v84
	v_min_f32_e32 v93, 0, v85
	v_min_f32_e32 v94, 0, v86
	v_min_f32_e32 v95, 0, v87
	v_min_f32_e32 v96, 0, v88
	v_min_f32_e32 v97, 0, v89
	v_min_f32_e32 v98, 0, v90
	v_min_f32_e32 v99, 0, v91
	v_sub_f32_e32 v92, v92, v242
	v_sub_f32_e32 v93, v93, v243
	v_sub_f32_e32 v94, v94, v244
	v_sub_f32_e32 v95, v95, v245
	v_sub_f32_e32 v96, v96, v246
	v_sub_f32_e32 v97, v97, v247
	v_sub_f32_e32 v98, v98, v248
	v_sub_f32_e32 v99, v99, v249
	v_mul_f32_e32 v92, 0x3d800000, v92
	v_mul_f32_e32 v93, 0x3d800000, v93
	v_mul_f32_e32 v94, 0x3d800000, v94
	v_mul_f32_e32 v95, 0x3d800000, v95
	v_mul_f32_e32 v96, 0x3d800000, v96
	v_mul_f32_e32 v97, 0x3d800000, v97
	v_mul_f32_e32 v98, 0x3d800000, v98
	v_mul_f32_e32 v99, 0x3d800000, v99
	v_add_f32_dpp v180, v92, v92 row_shr:1 row_mask:0xf bank_mask:0xf bound_ctrl:1
	v_add_f32_dpp v181, v93, v93 row_shr:1 row_mask:0xf bank_mask:0xf bound_ctrl:1
	v_add_f32_dpp v182, v94, v94 row_shr:1 row_mask:0xf bank_mask:0xf bound_ctrl:1
	v_add_f32_dpp v183, v95, v95 row_shr:1 row_mask:0xf bank_mask:0xf bound_ctrl:1
	v_add_f32_dpp v184, v96, v96 row_shr:1 row_mask:0xf bank_mask:0xf bound_ctrl:1
	v_add_f32_dpp v185, v97, v97 row_shr:1 row_mask:0xf bank_mask:0xf bound_ctrl:1
	v_add_f32_dpp v186, v98, v98 row_shr:1 row_mask:0xf bank_mask:0xf bound_ctrl:1
	v_add_f32_dpp v187, v99, v99 row_shr:1 row_mask:0xf bank_mask:0xf bound_ctrl:1
	v_add_f32_dpp v180, v180, v180 row_shr:2 row_mask:0xf bank_mask:0xf bound_ctrl:1
	v_add_f32_dpp v181, v181, v181 row_shr:2 row_mask:0xf bank_mask:0xf bound_ctrl:1
	v_add_f32_dpp v182, v182, v182 row_shr:2 row_mask:0xf bank_mask:0xf bound_ctrl:1
	v_add_f32_dpp v183, v183, v183 row_shr:2 row_mask:0xf bank_mask:0xf bound_ctrl:1
	v_add_f32_dpp v184, v184, v184 row_shr:2 row_mask:0xf bank_mask:0xf bound_ctrl:1
	v_add_f32_dpp v185, v185, v185 row_shr:2 row_mask:0xf bank_mask:0xf bound_ctrl:1
	v_add_f32_dpp v186, v186, v186 row_shr:2 row_mask:0xf bank_mask:0xf bound_ctrl:1
	v_add_f32_dpp v187, v187, v187 row_shr:2 row_mask:0xf bank_mask:0xf bound_ctrl:1
	v_add_f32_dpp v180, v180, v180 row_shr:4 row_mask:0xf bank_mask:0xf bound_ctrl:1
	v_add_f32_dpp v181, v181, v181 row_shr:4 row_mask:0xf bank_mask:0xf bound_ctrl:1
	v_add_f32_dpp v182, v182, v182 row_shr:4 row_mask:0xf bank_mask:0xf bound_ctrl:1
	v_add_f32_dpp v183, v183, v183 row_shr:4 row_mask:0xf bank_mask:0xf bound_ctrl:1
	v_add_f32_dpp v184, v184, v184 row_shr:4 row_mask:0xf bank_mask:0xf bound_ctrl:1
	v_add_f32_dpp v185, v185, v185 row_shr:4 row_mask:0xf bank_mask:0xf bound_ctrl:1
	v_add_f32_dpp v186, v186, v186 row_shr:4 row_mask:0xf bank_mask:0xf bound_ctrl:1
	v_add_f32_dpp v187, v187, v187 row_shr:4 row_mask:0xf bank_mask:0xf bound_ctrl:1
	v_add_f32_dpp v180, v180, v180 row_shr:8 row_mask:0xf bank_mask:0xf bound_ctrl:1
	v_add_f32_dpp v181, v181, v181 row_shr:8 row_mask:0xf bank_mask:0xf bound_ctrl:1
	v_add_f32_dpp v182, v182, v182 row_shr:8 row_mask:0xf bank_mask:0xf bound_ctrl:1
	v_add_f32_dpp v183, v183, v183 row_shr:8 row_mask:0xf bank_mask:0xf bound_ctrl:1
	v_add_f32_dpp v184, v184, v184 row_shr:8 row_mask:0xf bank_mask:0xf bound_ctrl:1
	v_add_f32_dpp v185, v185, v185 row_shr:8 row_mask:0xf bank_mask:0xf bound_ctrl:1
	v_add_f32_dpp v186, v186, v186 row_shr:8 row_mask:0xf bank_mask:0xf bound_ctrl:1
	v_add_f32_dpp v187, v187, v187 row_shr:8 row_mask:0xf bank_mask:0xf bound_ctrl:1
	v_add_f32_dpp v180, v180, v180 row_bcast:15 row_mask:0xa bank_mask:0xf
	v_add_f32_dpp v181, v181, v181 row_bcast:15 row_mask:0xa bank_mask:0xf
	v_add_f32_dpp v182, v182, v182 row_bcast:15 row_mask:0xa bank_mask:0xf
	v_add_f32_dpp v183, v183, v183 row_bcast:15 row_mask:0xa bank_mask:0xf
	v_add_f32_dpp v184, v184, v184 row_bcast:15 row_mask:0xa bank_mask:0xf
	v_add_f32_dpp v185, v185, v185 row_bcast:15 row_mask:0xa bank_mask:0xf
	v_add_f32_dpp v186, v186, v186 row_bcast:15 row_mask:0xa bank_mask:0xf
	v_add_f32_dpp v187, v187, v187 row_bcast:15 row_mask:0xa bank_mask:0xf
	v_add_f32_dpp v180, v180, v180 row_bcast:31 row_mask:0xc bank_mask:0xf
	v_add_f32_dpp v181, v181, v181 row_bcast:31 row_mask:0xc bank_mask:0xf
	v_add_f32_dpp v182, v182, v182 row_bcast:31 row_mask:0xc bank_mask:0xf
	v_add_f32_dpp v183, v183, v183 row_bcast:31 row_mask:0xc bank_mask:0xf
	v_add_f32_dpp v184, v184, v184 row_bcast:31 row_mask:0xc bank_mask:0xf
	v_add_f32_dpp v185, v185, v185 row_bcast:31 row_mask:0xc bank_mask:0xf
	v_add_f32_dpp v186, v186, v186 row_bcast:31 row_mask:0xc bank_mask:0xf
	v_add_f32_dpp v187, v187, v187 row_bcast:31 row_mask:0xc bank_mask:0xf
	v_readlane_b32 s0, v180, 63
	v_readlane_b32 s10, v181, 63
	v_readlane_b32 s14, v182, 63
	v_readlane_b32 s15, v183, 63
	v_exp_f32_e32 v234, s0
	v_exp_f32_e32 v235, s10
	v_exp_f32_e32 v236, s14
	v_exp_f32_e32 v237, s15
	v_readlane_b32 s0, v184, 63
	v_readlane_b32 s10, v185, 63
	v_readlane_b32 s14, v186, 63
	v_readlane_b32 s15, v187, 63
	v_exp_f32_e32 v238, s0
	v_exp_f32_e32 v239, s10
	v_exp_f32_e32 v240, s14
	v_exp_f32_e32 v241, s15
	v_min_f32_e64 v242, -v180, s47
	v_min_f32_e64 v243, -v181, s47
	v_min_f32_e64 v244, -v182, s47
	v_min_f32_e64 v245, -v183, s47
	v_min_f32_e64 v246, -v184, s47
	v_min_f32_e64 v247, -v185, s47
	v_min_f32_e64 v248, -v186, s47
	v_min_f32_e64 v249, -v187, s47
	v_exp_f32_e32 v226, v242
	v_exp_f32_e32 v227, v243
	v_exp_f32_e32 v228, v244
	v_exp_f32_e32 v229, v245
	v_exp_f32_e32 v230, v246
	v_exp_f32_e32 v231, v247
	v_exp_f32_e32 v232, v248
	v_exp_f32_e32 v233, v249
	v_exp_f32_e32 v218, v180
	v_exp_f32_e32 v219, v181
	v_exp_f32_e32 v220, v182
	v_exp_f32_e32 v221, v183
	v_exp_f32_e32 v222, v184
	v_exp_f32_e32 v223, v185
	v_exp_f32_e32 v224, v186
	v_exp_f32_e32 v225, v187
	v_pk_mul_f32 v[242:243], v[202:203], v[226:227]
	v_pk_mul_f32 v[244:245], v[204:205], v[228:229]
	v_pk_mul_f32 v[246:247], v[206:207], v[230:231]
	v_pk_mul_f32 v[248:249], v[208:209], v[232:233]
	v_pk_mul_f32 v[92:93], v[242:243], v[234:235]
	v_pk_mul_f32 v[94:95], v[244:245], v[236:237]
	v_pk_mul_f32 v[96:97], v[246:247], v[238:239]
	v_pk_mul_f32 v[98:99], v[248:249], v[240:241]
	v_cvt_pk_bf16_f32 v48, v92, v93
	v_cvt_pk_bf16_f32 v49, v94, v95
	v_cvt_pk_bf16_f32 v50, v96, v97
	v_cvt_pk_bf16_f32 v51, v98, v99
	ds_write_b128 v61, v[48:51] offset:16
	s_add_i32 s48, s45, s36
	s_lshl_b32 s48, s48, 8
	s_add_u32 s48, s38, s48
	s_addc_u32 s49, s39, 0
	s_mov_b64 exec, s[16:17]
	global_store_dwordx4 v65, v[234:237], s[48:49] offset:32
	global_store_dwordx4 v65, v[238:241], s[48:49] offset:48
	s_mov_b64 exec, -1
	s_cmp_gt_i32 s36, 3
	s_cbranch_scc0 .Lgla_noq_2
	v_pk_mul_f32 v[218:219], v[210:211], v[218:219]
	v_pk_mul_f32 v[220:221], v[212:213], v[220:221]
	v_pk_mul_f32 v[222:223], v[214:215], v[222:223]
	v_pk_mul_f32 v[224:225], v[216:217], v[224:225]
	v_cvt_pk_bf16_f32 v52, v218, v219
	v_cvt_pk_bf16_f32 v53, v220, v221
	v_cvt_pk_bf16_f32 v54, v222, v223
	v_cvt_pk_bf16_f32 v55, v224, v225
	v_cvt_pk_bf16_f32 v56, v242, v243
	v_cvt_pk_bf16_f32 v57, v244, v245
	v_cvt_pk_bf16_f32 v58, v246, v247
	v_cvt_pk_bf16_f32 v59, v248, v249
	s_add_u32 s48, s4, 0x0
	s_addc_u32 s49, s5, 0
	global_store_dwordx4 v62, v[52:55], s[48:49] offset:16
	s_add_u32 s48, s4, 0x2000
	s_addc_u32 s49, s5, 0
	global_store_dwordx4 v62, v[56:59], s[48:49] offset:16
.Lgla_noq_2:
	ds_read_b128 v[132:135], v60 offset:4128
	ds_read_b128 v[136:139], v60 offset:4144
	ds_read_b128 v[140:143], v60 offset:4384
	ds_read_b128 v[144:147], v60 offset:4400
	ds_read_b128 v[148:151], v60 offset:4640
	ds_read_b128 v[152:155], v60 offset:4656
	ds_read_b128 v[156:159], v60 offset:4896
	ds_read_b128 v[160:163], v60 offset:4912
	ds_read_b128 v[164:167], v60 offset:5152
	ds_read_b128 v[168:171], v60 offset:5168
	ds_read_b128 v[172:175], v60 offset:5408
	ds_read_b128 v[176:179], v60 offset:5424
	v_pk_mul_f32 v[84:85], v[124:125], s[12:13] op_sel_hi:[1,0]
	v_pk_mul_f32 v[86:87], v[126:127], s[12:13] op_sel_hi:[1,0]
	v_pk_mul_f32 v[88:89], v[128:129], s[12:13] op_sel_hi:[1,0]
	v_pk_mul_f32 v[90:91], v[130:131], s[12:13] op_sel_hi:[1,0]
	s_waitcnt lgkmcnt(11)
	v_pk_fma_f32 v[84:85], v[12:13], v[132:133], v[84:85] op_sel_hi:[0,1,1]
	v_pk_fma_f32 v[86:87], v[12:13], v[134:135], v[86:87] op_sel_hi:[0,1,1]
	ds_read_b128 v[132:135], v60 offset:5664
	s_waitcnt lgkmcnt(11)
	v_pk_fma_f32 v[88:89], v[12:13], v[136:137], v[88:89] op_sel_hi:[0,1,1]
	v_pk_fma_f32 v[90:91], v[12:13], v[138:139], v[90:91] op_sel_hi:[0,1,1]
	ds_read_b128 v[136:139], v60 offset:5680
	s_waitcnt lgkmcnt(11)
	v_pk_fma_f32 v[84:85], v[12:13], v[140:141], v[84:85] op_sel:[1,0,0]
	v_pk_fma_f32 v[86:87], v[12:13], v[142:143], v[86:87] op_sel:[1,0,0]
	ds_read_b128 v[140:143], v60 offset:5920
	s_waitcnt lgkmcnt(11)
	v_pk_fma_f32 v[88:89], v[12:13], v[144:145], v[88:89] op_sel:[1,0,0]
	v_pk_fma_f32 v[90:91], v[12:13], v[146:147], v[90:91] op_sel:[1,0,0]
	ds_read_b128 v[144:147], v60 offset:5936
	s_waitcnt lgkmcnt(11)
	v_pk_fma_f32 v[84:85], v[14:15], v[148:149], v[84:85] op_sel_hi:[0,1,1]
	v_pk_fma_f32 v[86:87], v[14:15], v[150:151], v[86:87] op_sel_hi:[0,1,1]
	ds_read_b128 v[148:151], v60 offset:6176
	s_waitcnt lgkmcnt(11)
	v_pk_fma_f32 v[88:89], v[14:15], v[152:153], v[88:89] op_sel_hi:[0,1,1]
	v_pk_fma_f32 v[90:91], v[14:15], v[154:155], v[90:91] op_sel_hi:[0,1,1]
	ds_read_b128 v[152:155], v60 offset:6192
	s_waitcnt lgkmcnt(11)
	v_pk_fma_f32 v[84:85], v[14:15], v[156:157], v[84:85] op_sel:[1,0,0]
	v_pk_fma_f32 v[86:87], v[14:15], v[158:159], v[86:87] op_sel:[1,0,0]
	ds_read_b128 v[156:159], v60 offset:6432
	s_waitcnt lgkmcnt(11)
	v_pk_fma_f32 v[88:89], v[14:15], v[160:161], v[88:89] op_sel:[1,0,0]
	v_pk_fma_f32 v[90:91], v[14:15], v[162:163], v[90:91] op_sel:[1,0,0]
	ds_read_b128 v[160:163], v60 offset:6448
	s_waitcnt lgkmcnt(11)
	v_pk_fma_f32 v[84:85], v[8:9], v[164:165], v[84:85] op_sel_hi:[0,1,1]
	v_pk_fma_f32 v[86:87], v[8:9], v[166:167], v[86:87] op_sel_hi:[0,1,1]
	ds_read_b128 v[164:167], v60 offset:6688
	s_waitcnt lgkmcnt(11)
	v_pk_fma_f32 v[88:89], v[8:9], v[168:169], v[88:89] op_sel_hi:[0,1,1]
	v_pk_fma_f32 v[90:91], v[8:9], v[170:171], v[90:91] op_sel_hi:[0,1,1]
	ds_read_b128 v[168:171], v60 offset:6704
	s_waitcnt lgkmcnt(11)
	v_pk_fma_f32 v[84:85], v[8:9], v[172:173], v[84:85] op_sel:[1,0,0]
	v_pk_fma_f32 v[86:87], v[8:9], v[174:175], v[86:87] op_sel:[1,0,0]
	ds_read_b128 v[172:175], v60 offset:6944
	s_waitcnt lgkmcnt(11)
	v_pk_fma_f32 v[88:89], v[8:9], v[176:177], v[88:89] op_sel:[1,0,0]
	v_pk_fma_f32 v[90:91], v[8:9], v[178:179], v[90:91] op_sel:[1,0,0]
	ds_read_b128 v[176:179], v60 offset:6960
	s_waitcnt lgkmcnt(11)
	v_pk_fma_f32 v[84:85], v[10:11], v[132:133], v[84:85] op_sel_hi:[0,1,1]
	v_pk_fma_f32 v[86:87], v[10:11], v[134:135], v[86:87] op_sel_hi:[0,1,1]
	ds_read_b128 v[132:135], v60 offset:7200
	s_waitcnt lgkmcnt(11)
	v_pk_fma_f32 v[88:89], v[10:11], v[136:137], v[88:89] op_sel_hi:[0,1,1]
	v_pk_fma_f32 v[90:91], v[10:11], v[138:139], v[90:91] op_sel_hi:[0,1,1]
	ds_read_b128 v[136:139], v60 offset:7216
	s_waitcnt lgkmcnt(11)
	v_pk_fma_f32 v[84:85], v[10:11], v[140:141], v[84:85] op_sel:[1,0,0]
	v_pk_fma_f32 v[86:87], v[10:11], v[142:143], v[86:87] op_sel:[1,0,0]
	ds_read_b128 v[140:143], v60 offset:7456
	s_waitcnt lgkmcnt(11)
	v_pk_fma_f32 v[88:89], v[10:11], v[144:145], v[88:89] op_sel:[1,0,0]
	v_pk_fma_f32 v[90:91], v[10:11], v[146:147], v[90:91] op_sel:[1,0,0]
	ds_read_b128 v[144:147], v60 offset:7472
	s_waitcnt lgkmcnt(11)
	v_pk_fma_f32 v[84:85], v[4:5], v[148:149], v[84:85] op_sel_hi:[0,1,1]
	v_pk_fma_f32 v[86:87], v[4:5], v[150:151], v[86:87] op_sel_hi:[0,1,1]
	ds_read_b128 v[148:151], v60 offset:7712
	s_waitcnt lgkmcnt(11)
	v_pk_fma_f32 v[88:89], v[4:5], v[152:153], v[88:89] op_sel_hi:[0,1,1]
	v_pk_fma_f32 v[90:91], v[4:5], v[154:155], v[90:91] op_sel_hi:[0,1,1]
	ds_read_b128 v[152:155], v60 offset:7728
	s_waitcnt lgkmcnt(11)
	v_pk_fma_f32 v[84:85], v[4:5], v[156:157], v[84:85] op_sel:[1,0,0]
	v_pk_fma_f32 v[86:87], v[4:5], v[158:159], v[86:87] op_sel:[1,0,0]
	ds_read_b128 v[156:159], v60 offset:7968
	s_waitcnt lgkmcnt(11)
	v_pk_fma_f32 v[88:89], v[4:5], v[160:161], v[88:89] op_sel:[1,0,0]
	v_pk_fma_f32 v[90:91], v[4:5], v[162:163], v[90:91] op_sel:[1,0,0]
	ds_read_b128 v[160:163], v60 offset:7984
	s_waitcnt lgkmcnt(11)
	v_pk_fma_f32 v[84:85], v[6:7], v[164:165], v[84:85] op_sel_hi:[0,1,1]
	v_pk_fma_f32 v[86:87], v[6:7], v[166:167], v[86:87] op_sel_hi:[0,1,1]
	s_waitcnt lgkmcnt(10)
	v_pk_fma_f32 v[88:89], v[6:7], v[168:169], v[88:89] op_sel_hi:[0,1,1]
	v_pk_fma_f32 v[90:91], v[6:7], v[170:171], v[90:91] op_sel_hi:[0,1,1]
	s_waitcnt lgkmcnt(9)
	v_pk_fma_f32 v[84:85], v[6:7], v[172:173], v[84:85] op_sel:[1,0,0]
	v_pk_fma_f32 v[86:87], v[6:7], v[174:175], v[86:87] op_sel:[1,0,0]
	s_waitcnt lgkmcnt(8)
	v_pk_fma_f32 v[88:89], v[6:7], v[176:177], v[88:89] op_sel:[1,0,0]
	v_pk_fma_f32 v[90:91], v[6:7], v[178:179], v[90:91] op_sel:[1,0,0]
	s_waitcnt lgkmcnt(7)
	v_pk_fma_f32 v[84:85], v[0:1], v[132:133], v[84:85] op_sel_hi:[0,1,1]
	v_pk_fma_f32 v[86:87], v[0:1], v[134:135], v[86:87] op_sel_hi:[0,1,1]
	s_waitcnt lgkmcnt(6)
	v_pk_fma_f32 v[88:89], v[0:1], v[136:137], v[88:89] op_sel_hi:[0,1,1]
	v_pk_fma_f32 v[90:91], v[0:1], v[138:139], v[90:91] op_sel_hi:[0,1,1]
	s_waitcnt lgkmcnt(5)
	v_pk_fma_f32 v[84:85], v[0:1], v[140:141], v[84:85] op_sel:[1,0,0]
	v_pk_fma_f32 v[86:87], v[0:1], v[142:143], v[86:87] op_sel:[1,0,0]
	s_waitcnt lgkmcnt(4)
	v_pk_fma_f32 v[88:89], v[0:1], v[144:145], v[88:89] op_sel:[1,0,0]
	v_pk_fma_f32 v[90:91], v[0:1], v[146:147], v[90:91] op_sel:[1,0,0]
	s_waitcnt lgkmcnt(3)
	v_pk_fma_f32 v[84:85], v[2:3], v[148:149], v[84:85] op_sel_hi:[0,1,1]
	v_pk_fma_f32 v[86:87], v[2:3], v[150:151], v[86:87] op_sel_hi:[0,1,1]
	s_waitcnt lgkmcnt(2)
	v_pk_fma_f32 v[88:89], v[2:3], v[152:153], v[88:89] op_sel_hi:[0,1,1]
	v_pk_fma_f32 v[90:91], v[2:3], v[154:155], v[90:91] op_sel_hi:[0,1,1]
	s_waitcnt lgkmcnt(1)
	v_pk_fma_f32 v[84:85], v[2:3], v[156:157], v[84:85] op_sel:[1,0,0]
	v_pk_fma_f32 v[86:87], v[2:3], v[158:159], v[86:87] op_sel:[1,0,0]
	s_waitcnt lgkmcnt(0)
	v_pk_fma_f32 v[88:89], v[2:3], v[160:161], v[88:89] op_sel:[1,0,0]
	v_pk_fma_f32 v[90:91], v[2:3], v[162:163], v[90:91] op_sel:[1,0,0]
	v_exp_f32_e64 v242, -|v84|
	v_exp_f32_e64 v243, -|v85|
	v_exp_f32_e64 v244, -|v86|
	v_exp_f32_e64 v245, -|v87|
	v_exp_f32_e64 v246, -|v88|
	v_exp_f32_e64 v247, -|v89|
	v_exp_f32_e64 v248, -|v90|
	v_exp_f32_e64 v249, -|v91|
	v_add_f32_e32 v242, 1.0, v242
	v_add_f32_e32 v243, 1.0, v243
	v_add_f32_e32 v244, 1.0, v244
	v_add_f32_e32 v245, 1.0, v245
	v_add_f32_e32 v246, 1.0, v246
	v_add_f32_e32 v247, 1.0, v247
	v_add_f32_e32 v248, 1.0, v248
	v_add_f32_e32 v249, 1.0, v249
	v_log_f32_e32 v242, v242
	v_log_f32_e32 v243, v243
	v_log_f32_e32 v244, v244
	v_log_f32_e32 v245, v245
	v_log_f32_e32 v246, v246
	v_log_f32_e32 v247, v247
	v_log_f32_e32 v248, v248
	v_log_f32_e32 v249, v249
	v_min_f32_e32 v92, 0, v84
	v_min_f32_e32 v93, 0, v85
	v_min_f32_e32 v94, 0, v86
	v_min_f32_e32 v95, 0, v87
	v_min_f32_e32 v96, 0, v88
	v_min_f32_e32 v97, 0, v89
	v_min_f32_e32 v98, 0, v90
	v_min_f32_e32 v99, 0, v91
	v_sub_f32_e32 v92, v92, v242
	v_sub_f32_e32 v93, v93, v243
	v_sub_f32_e32 v94, v94, v244
	v_sub_f32_e32 v95, v95, v245
	v_sub_f32_e32 v96, v96, v246
	v_sub_f32_e32 v97, v97, v247
	v_sub_f32_e32 v98, v98, v248
	v_sub_f32_e32 v99, v99, v249
	v_mul_f32_e32 v92, 0x3d800000, v92
	v_mul_f32_e32 v93, 0x3d800000, v93
	v_mul_f32_e32 v94, 0x3d800000, v94
	v_mul_f32_e32 v95, 0x3d800000, v95
	v_mul_f32_e32 v96, 0x3d800000, v96
	v_mul_f32_e32 v97, 0x3d800000, v97
	v_mul_f32_e32 v98, 0x3d800000, v98
	v_mul_f32_e32 v99, 0x3d800000, v99
	v_add_f32_dpp v180, v92, v92 row_shr:1 row_mask:0xf bank_mask:0xf bound_ctrl:1
	v_add_f32_dpp v181, v93, v93 row_shr:1 row_mask:0xf bank_mask:0xf bound_ctrl:1
	v_add_f32_dpp v182, v94, v94 row_shr:1 row_mask:0xf bank_mask:0xf bound_ctrl:1
	v_add_f32_dpp v183, v95, v95 row_shr:1 row_mask:0xf bank_mask:0xf bound_ctrl:1
	v_add_f32_dpp v184, v96, v96 row_shr:1 row_mask:0xf bank_mask:0xf bound_ctrl:1
	v_add_f32_dpp v185, v97, v97 row_shr:1 row_mask:0xf bank_mask:0xf bound_ctrl:1
	v_add_f32_dpp v186, v98, v98 row_shr:1 row_mask:0xf bank_mask:0xf bound_ctrl:1
	v_add_f32_dpp v187, v99, v99 row_shr:1 row_mask:0xf bank_mask:0xf bound_ctrl:1
	v_add_f32_dpp v180, v180, v180 row_shr:2 row_mask:0xf bank_mask:0xf bound_ctrl:1
	v_add_f32_dpp v181, v181, v181 row_shr:2 row_mask:0xf bank_mask:0xf bound_ctrl:1
	v_add_f32_dpp v182, v182, v182 row_shr:2 row_mask:0xf bank_mask:0xf bound_ctrl:1
	v_add_f32_dpp v183, v183, v183 row_shr:2 row_mask:0xf bank_mask:0xf bound_ctrl:1
	v_add_f32_dpp v184, v184, v184 row_shr:2 row_mask:0xf bank_mask:0xf bound_ctrl:1
	v_add_f32_dpp v185, v185, v185 row_shr:2 row_mask:0xf bank_mask:0xf bound_ctrl:1
	v_add_f32_dpp v186, v186, v186 row_shr:2 row_mask:0xf bank_mask:0xf bound_ctrl:1
	v_add_f32_dpp v187, v187, v187 row_shr:2 row_mask:0xf bank_mask:0xf bound_ctrl:1
	v_add_f32_dpp v180, v180, v180 row_shr:4 row_mask:0xf bank_mask:0xf bound_ctrl:1
	v_add_f32_dpp v181, v181, v181 row_shr:4 row_mask:0xf bank_mask:0xf bound_ctrl:1
	v_add_f32_dpp v182, v182, v182 row_shr:4 row_mask:0xf bank_mask:0xf bound_ctrl:1
	v_add_f32_dpp v183, v183, v183 row_shr:4 row_mask:0xf bank_mask:0xf bound_ctrl:1
	v_add_f32_dpp v184, v184, v184 row_shr:4 row_mask:0xf bank_mask:0xf bound_ctrl:1
	v_add_f32_dpp v185, v185, v185 row_shr:4 row_mask:0xf bank_mask:0xf bound_ctrl:1
	v_add_f32_dpp v186, v186, v186 row_shr:4 row_mask:0xf bank_mask:0xf bound_ctrl:1
	v_add_f32_dpp v187, v187, v187 row_shr:4 row_mask:0xf bank_mask:0xf bound_ctrl:1
	v_add_f32_dpp v180, v180, v180 row_shr:8 row_mask:0xf bank_mask:0xf bound_ctrl:1
	v_add_f32_dpp v181, v181, v181 row_shr:8 row_mask:0xf bank_mask:0xf bound_ctrl:1
	v_add_f32_dpp v182, v182, v182 row_shr:8 row_mask:0xf bank_mask:0xf bound_ctrl:1
	v_add_f32_dpp v183, v183, v183 row_shr:8 row_mask:0xf bank_mask:0xf bound_ctrl:1
	v_add_f32_dpp v184, v184, v184 row_shr:8 row_mask:0xf bank_mask:0xf bound_ctrl:1
	v_add_f32_dpp v185, v185, v185 row_shr:8 row_mask:0xf bank_mask:0xf bound_ctrl:1
	v_add_f32_dpp v186, v186, v186 row_shr:8 row_mask:0xf bank_mask:0xf bound_ctrl:1
	v_add_f32_dpp v187, v187, v187 row_shr:8 row_mask:0xf bank_mask:0xf bound_ctrl:1
	v_add_f32_dpp v180, v180, v180 row_bcast:15 row_mask:0xa bank_mask:0xf
	v_add_f32_dpp v181, v181, v181 row_bcast:15 row_mask:0xa bank_mask:0xf
	v_add_f32_dpp v182, v182, v182 row_bcast:15 row_mask:0xa bank_mask:0xf
	v_add_f32_dpp v183, v183, v183 row_bcast:15 row_mask:0xa bank_mask:0xf
	v_add_f32_dpp v184, v184, v184 row_bcast:15 row_mask:0xa bank_mask:0xf
	v_add_f32_dpp v185, v185, v185 row_bcast:15 row_mask:0xa bank_mask:0xf
	v_add_f32_dpp v186, v186, v186 row_bcast:15 row_mask:0xa bank_mask:0xf
	v_add_f32_dpp v187, v187, v187 row_bcast:15 row_mask:0xa bank_mask:0xf
	v_add_f32_dpp v180, v180, v180 row_bcast:31 row_mask:0xc bank_mask:0xf
	v_add_f32_dpp v181, v181, v181 row_bcast:31 row_mask:0xc bank_mask:0xf
	v_add_f32_dpp v182, v182, v182 row_bcast:31 row_mask:0xc bank_mask:0xf
	v_add_f32_dpp v183, v183, v183 row_bcast:31 row_mask:0xc bank_mask:0xf
	v_add_f32_dpp v184, v184, v184 row_bcast:31 row_mask:0xc bank_mask:0xf
	v_add_f32_dpp v185, v185, v185 row_bcast:31 row_mask:0xc bank_mask:0xf
	v_add_f32_dpp v186, v186, v186 row_bcast:31 row_mask:0xc bank_mask:0xf
	v_add_f32_dpp v187, v187, v187 row_bcast:31 row_mask:0xc bank_mask:0xf
	v_readlane_b32 s0, v180, 63
	v_readlane_b32 s10, v181, 63
	v_readlane_b32 s14, v182, 63
	v_readlane_b32 s15, v183, 63
	v_sub_f32_e32 v242, s0, v180
	v_sub_f32_e32 v243, s10, v181
	v_sub_f32_e32 v244, s14, v182
	v_sub_f32_e32 v245, s15, v183
	v_readlane_b32 s0, v184, 63
	v_readlane_b32 s10, v185, 63
	v_readlane_b32 s14, v186, 63
	v_readlane_b32 s15, v187, 63
	v_sub_f32_e32 v246, s0, v184
	v_sub_f32_e32 v247, s10, v185
	v_sub_f32_e32 v248, s14, v186
	v_sub_f32_e32 v249, s15, v187
	v_add_f32_e32 v180, v242, v92
	v_add_f32_e32 v181, v243, v93
	v_add_f32_e32 v182, v244, v94
	v_add_f32_e32 v183, v245, v95
	v_add_f32_e32 v184, v246, v96
	v_add_f32_e32 v185, v247, v97
	v_add_f32_e32 v186, v248, v98
	v_add_f32_e32 v187, v249, v99
	v_readlane_b32 s0, v180, 0
	v_readlane_b32 s10, v181, 0
	v_readlane_b32 s14, v182, 0
	v_readlane_b32 s15, v183, 0
	v_exp_f32_e32 v234, s0
	v_exp_f32_e32 v235, s10
	v_exp_f32_e32 v236, s14
	v_exp_f32_e32 v237, s15
	v_readlane_b32 s0, v184, 0
	v_readlane_b32 s10, v185, 0
	v_readlane_b32 s14, v186, 0
	v_readlane_b32 s15, v187, 0
	v_exp_f32_e32 v238, s0
	v_exp_f32_e32 v239, s10
	v_exp_f32_e32 v240, s14
	v_exp_f32_e32 v241, s15
	v_min_f32_e64 v242, -v180, s47
	v_min_f32_e64 v243, -v181, s47
	v_min_f32_e64 v244, -v182, s47
	v_min_f32_e64 v245, -v183, s47
	v_min_f32_e64 v246, -v184, s47
	v_min_f32_e64 v247, -v185, s47
	v_min_f32_e64 v248, -v186, s47
	v_min_f32_e64 v249, -v187, s47
	v_exp_f32_e32 v226, v242
	v_exp_f32_e32 v227, v243
	v_exp_f32_e32 v228, v244
	v_exp_f32_e32 v229, v245
	v_exp_f32_e32 v230, v246
	v_exp_f32_e32 v231, v247
	v_exp_f32_e32 v232, v248
	v_exp_f32_e32 v233, v249
	v_exp_f32_e32 v218, v180
	v_exp_f32_e32 v219, v181
	v_exp_f32_e32 v220, v182
	v_exp_f32_e32 v221, v183
	v_exp_f32_e32 v222, v184
	v_exp_f32_e32 v223, v185
	v_exp_f32_e32 v224, v186
	v_exp_f32_e32 v225, v187
	v_pk_mul_f32 v[242:243], v[202:203], v[226:227]
	v_pk_mul_f32 v[244:245], v[204:205], v[228:229]
	v_pk_mul_f32 v[246:247], v[206:207], v[230:231]
	v_pk_mul_f32 v[248:249], v[208:209], v[232:233]
	v_pk_mul_f32 v[92:93], v[242:243], v[234:235]
	v_pk_mul_f32 v[94:95], v[244:245], v[236:237]
	v_pk_mul_f32 v[96:97], v[246:247], v[238:239]
	v_pk_mul_f32 v[98:99], v[248:249], v[240:241]
	v_cvt_pk_bf16_f32 v48, v92, v93
	v_cvt_pk_bf16_f32 v49, v94, v95
	v_cvt_pk_bf16_f32 v50, v96, v97
	v_cvt_pk_bf16_f32 v51, v98, v99
	ds_write_b128 v61, v[48:51] offset:12304
	s_add_i32 s48, s45, s1
	s_addk_i32 s48, 0x84
	s_lshl_b32 s48, s48, 8
	s_add_u32 s48, s38, s48
	s_addc_u32 s49, s39, 0
	s_mov_b64 exec, s[16:17]
	global_store_dwordx4 v65, v[234:237], s[48:49] offset:32
	global_store_dwordx4 v65, v[238:241], s[48:49] offset:48
	s_mov_b64 exec, -1
	s_cmp_gt_i32 s36, 3
	s_cbranch_scc0 .Lgla_noq_3
	v_pk_mul_f32 v[218:219], v[210:211], v[218:219]
	v_pk_mul_f32 v[220:221], v[212:213], v[220:221]
	v_pk_mul_f32 v[222:223], v[214:215], v[222:223]
	v_pk_mul_f32 v[224:225], v[216:217], v[224:225]
	v_cvt_pk_bf16_f32 v52, v218, v219
	v_cvt_pk_bf16_f32 v53, v220, v221
	v_cvt_pk_bf16_f32 v54, v222, v223
	v_cvt_pk_bf16_f32 v55, v224, v225
	v_cvt_pk_bf16_f32 v56, v242, v243
	v_cvt_pk_bf16_f32 v57, v244, v245
	v_cvt_pk_bf16_f32 v58, v246, v247
	v_cvt_pk_bf16_f32 v59, v248, v249
	s_add_u32 s48, s4, 0x4000
	s_addc_u32 s49, s5, 0
	global_store_dwordx4 v62, v[52:55], s[48:49] offset:16
	s_add_u32 s48, s4, 0x6000
	s_addc_u32 s49, s5, 0
	global_store_dwordx4 v62, v[56:59], s[48:49] offset:16
.Lgla_noq_3:
	s_lshr_b32 s0, s37, 6
	s_branch .LBB0_329
